# GLA g1 tile LDS layout: conflict-free ds_read2st64_b32 for the log-decay MFMA A operands (was 8-way bank conflicted)
# baseline (speedup 1.0000x reference)
.LBB0_448:
	v_lshrrev_b32_e32 v250, 6, v154
	v_bfe_u32 v251, v154, 2, 2
	v_lshlrev_b32_e32 v250, 4, v250
	v_lshl_add_u32 v250, v251, 2, v250
	v_and_b32_e32 v251, 3, v154
	v_lshl_add_u32 v250, v251, 8, v250
	v_bfe_u32 v251, v154, 4, 2
	v_lshl_add_u32 v250, v251, 10, v250
	v_mov_b32_e32 v0, 0
	ds_read_b128 v[2:5], v0 offset:80
	ds_read_b64 v[6:7], v0 offset:216
	v_readlane_b32 s2, v240, 0
	s_cmpk_gt_i32 s2, 0x1ff
	s_waitcnt lgkmcnt(0)
	v_readfirstlane_b32 s35, v3
	v_readfirstlane_b32 s34, v2
	v_readfirstlane_b32 s37, v5
	v_readfirstlane_b32 s36, v4
	v_readfirstlane_b32 s39, v7
	v_readfirstlane_b32 s38, v6
	s_cbranch_scc1 .LBB0_511
	v_lshrrev_b32_e32 v8, 4, v154
	s_movk_i32 s14, 0xf0
	v_mul_u32_u24_e32 v9, 0x1800, v8
	v_lshlrev_b32_e32 v2, 4, v154
	v_lshrrev_b32_e32 v4, 2, v154
	v_and_b32_e32 v7, 3, v154
	v_and_or_b32 v112, v2, s14, v9
	v_lshrrev_b32_e32 v9, 5, v154
	v_lshlrev_b32_e32 v12, 3, v154
	s_mov_b32 s6, 0x16400
	v_bfe_u32 v15, v154, 2, 2
	v_lshrrev_b32_e32 v16, 1, v154
	v_and_b32_e32 v3, 15, v154
	v_bfe_u32 v5, v154, 4, 2
	v_and_b32_e32 v6, 0xf0, v4
	v_lshlrev_b32_e32 v123, 4, v7
	v_mul_u32_u24_e32 v10, 0x1800, v9
	v_and_b32_e32 v11, 0x1f0, v2
	v_and_b32_e32 v13, 0x78, v12
	s_addk_i32 s6, 0xf0
	v_and_or_b32 v15, v16, 24, v15
	v_and_b32_e32 v16, 0x3c0, v154
	v_and_b32_e32 v12, 24, v12
	s_movk_i32 s15, 0x110
	v_mov_b32_e32 v28, 0x2200
	v_or_b32_e32 v122, v6, v3
	v_lshl_or_b32 v110, v4, 7, v123
	v_or_b32_e32 v114, v10, v11
	v_lshlrev_b32_e32 v124, 6, v4
	v_lshlrev_b32_e32 v4, 2, v154
	v_lshlrev_b32_e32 v6, 2, v6
	v_lshlrev_b32_e32 v10, 2, v3
	v_add_u32_e32 v11, s6, v11
	v_add3_u32 v17, s6, v16, v12
	v_cmp_eq_u32_e64 s[6:7], 3, v5
	v_mul_u32_u24_e32 v26, 0x210, v15
	v_mul_u32_u24_e32 v27, 0x110, v15
	v_mad_u32_u24 v15, v15, s15, v28
	v_lshlrev_b32_e32 v129, 9, v5
	v_lshlrev_b32_e32 v28, 11, v3
	v_lshlrev_b32_e32 v133, 2, v5
	v_lshlrev_b32_e32 v5, 3, v5
	v_and_or_b32 v7, v4, 48, v7
	v_add3_u32 v6, s14, v6, v10
	v_or3_b32 v116, v16, v5, v28
	v_add3_u32 v10, s14, v16, v10
	v_lshrrev_b32_e32 v16, 3, v154
	s_movk_i32 s14, 0x70
	v_lshlrev_b32_e32 v126, 6, v7
	v_and_b32_e32 v7, 48, v154
	v_mov_b32_e32 v14, 0xf0
	v_and_or_b32 v16, v16, s14, v3
	s_mov_b32 s14, 0x1e800
	v_lshl_add_u32 v14, v13, 2, v14
	v_lshlrev_b32_e32 v13, 1, v13
	v_add_u32_e32 v128, 0xf0, v7
	v_add_u32_e32 v20, 0x200, v154
	v_mul_u32_u24_e32 v28, 0x90, v16
	s_addk_i32 s14, 0xf0
	v_sub_u32_e32 v13, v14, v13
	v_lshrrev_b32_e32 v21, 4, v20
	v_add3_u32 v28, s14, v28, v5
	v_sub_u32_e32 v29, v128, v5
	v_mul_u32_u24_e32 v5, 0x88, v8
	v_mul_u32_u24_e32 v24, 0x210, v9
	v_and_b32_e32 v9, 2, v9
	v_lshl_add_u32 v135, v5, 1, v13
	v_mul_u32_u24_e32 v5, 0x88, v21
	v_lshl_add_u32 v136, v5, 1, v13
	v_lshlrev_b32_e32 v5, 4, v9
	v_and_b32_e32 v1, 63, v154
	v_lshlrev_b32_e32 v18, 9, v8
	v_mul_u32_u24_e32 v19, 0x110, v8
	v_or_b32_e32 v8, v5, v3
	v_or_b32_e32 v5, v5, v133
	v_cmp_gt_u32_e64 s[8:9], 32, v1
	v_cmp_gt_u32_e64 s[10:11], 16, v1
	v_cmp_lt_u32_e64 s[12:13], 31, v1
	v_lshlrev_b32_e32 v1, 9, v7
	v_lshlrev_b32_e32 v22, 9, v21
	v_mul_u32_u24_e32 v23, 0x110, v21
	v_mad_u32_u24 v134, v16, s15, v128
	v_add_u32_e32 v7, s14, v7
	v_cmp_gt_u32_e64 s[14:15], v5, v16
	v_cmp_lt_u32_e64 s[16:17], v5, v16
	v_or_b32_e32 v21, 2, v5
	v_or_b32_e32 v5, 3, v5
	v_cmp_gt_u32_e64 s[20:21], v5, v16
	v_or_b32_e32 v5, 1, v9
	v_cmp_gt_u32_e64 s[18:19], v21, v16
	v_lshlrev_b32_e32 v21, 5, v9
	v_lshlrev_b32_e32 v9, 4, v5
	v_or_b32_e32 v30, v9, v3
	v_or_b32_e32 v9, v9, v133
	v_cmp_gt_u32_e64 s[22:23], v9, v16
	v_cmp_lt_u32_e64 s[24:25], v9, v16
	v_or_b32_e32 v31, 2, v9
	v_or_b32_e32 v9, 3, v9
	v_cmp_gt_u32_e64 s[28:29], v9, v16
	v_lshlrev_b32_e32 v9, 5, v5
	v_mov_b32_e32 v5, v0
	v_add_u32_e32 v127, 0xf0, v4
	s_add_u32 s41, s38, 0x2100000
	v_lshl_add_u64 v[4:5], s[38:39], 0, v[4:5]
	s_mov_b64 s[30:31], 0xab20000
	s_addc_u32 s54, s39, 0
	v_lshl_add_u64 v[118:119], v[4:5], 0, s[30:31]
	v_mbcnt_lo_u32_b32 v4, -1, 0
	s_add_u32 s55, s38, 0xad20000
	v_mbcnt_hi_u32_b32 v4, -1, v4
	v_cmp_gt_u32_e64 s[26:27], v31, v16
	v_mul_u32_u24_e32 v16, 0x90, v3
	v_mul_u32_u24_e32 v31, 0x110, v3
	s_addc_u32 s56, s39, 0
	v_and_or_b32 v3, v4, 64, v3
	v_add_u32_e32 v25, 0x600, v154
	s_add_u32 s57, s38, 0x2920000
	v_lshlrev_b32_e32 v137, 2, v3
	v_mov_b32_e32 v3, v0
	v_lshrrev_b32_e32 v20, 5, v20
	v_lshrrev_b32_e32 v25, 5, v25
	s_addc_u32 s58, s39, 0
	v_lshl_add_u64 v[2:3], s[38:39], 0, v[2:3]
	s_mov_b64 s[30:31], 0x6b20000
	s_movk_i32 s2, 0x100
	s_movk_i32 s4, 0x80
	v_add_u32_e32 v12, 0xf0, v12
	v_mul_u32_u24_e32 v20, 0x210, v20
	v_mul_u32_u24_e32 v25, 0x210, v25
	v_mul_u32_u24_e32 v8, 0x110, v8
	v_mul_u32_u24_e32 v30, 0x110, v30
	v_lshl_add_u64 v[120:121], v[2:3], 0, s[30:31]
	s_add_u32 s60, s38, 0xad20800
	s_mov_b32 s66, 0x12000
	v_readlane_b32 s30, v240, 0
	v_cmp_gt_u32_e64 s[2:3], s2, v154
	v_mov_b32_e32 v111, v0
	v_add_u32_e32 v125, 0xf0, v124
	v_mov_b32_e32 v113, v0
	v_mov_b32_e32 v115, v0
	v_cmp_gt_u32_e64 s[4:5], s4, v154
	v_or_b32_e32 v130, 0x800, v129
	v_or_b32_e32 v131, 0x1000, v129
	v_or_b32_e32 v132, 0x1800, v129
	v_mov_b32_e32 v117, v0
	s_mov_b32 s59, 0
	v_or_b32_e32 v138, 64, v137
	v_or_b32_e32 v139, 0x80, v137
	v_or_b32_e32 v140, 0xc0, v137
	s_addc_u32 s61, s39, 0
	s_mov_b32 s62, 0x8000
	s_mov_b32 s63, 0x30000
	s_mov_b32 s64, 0x18000
	s_mov_b32 s65, 0x48000
	s_add_i32 s67, s66, 0xf0
	s_mov_b32 s68, 0xbfb8aa3b
	s_mov_b32 s69, 0xa000
	s_mov_b32 s70, 0xc000
	s_mov_b32 s71, 0xe000
	s_mov_b32 s72, 0x10000
	s_mov_b32 s73, 0x14000
	s_mov_b32 s74, 0x16000
	s_mov_b32 s75, 0x1a000
	v_add_u32_e32 v141, v10, v1
	s_mov_b32 s40, 0x3db504f3
	v_add_u32_e32 v142, v128, v8
	v_add_u32_e32 v143, v28, v21
	v_add_u32_e32 v144, v128, v30
	v_add_u32_e32 v145, v28, v9
	v_add_u32_e32 v146, v7, v16
	v_add_u32_e32 v147, v29, v31
	v_add_u32_e32 v148, v6, v1
	v_add_u32_e32 v149, v14, v18
	v_add_u32_e32 v150, v13, v19
	v_add_u32_e32 v151, v14, v22
	v_add_u32_e32 v152, v13, v23
	v_add_u32_e32 v153, v11, v24
	v_add_u32_e32 v155, v11, v20
	v_add_u32_e32 v156, v11, v25
	v_add_u32_e32 v157, v17, v26
	v_add_u32_e32 v158, v12, v27
	v_add_u32_e32 v159, v12, v15
	s_mov_b32 s42, s30
	s_branch .LBB0_452

.LBB0_458:
	s_or_b64 exec, exec, s[50:51]
	s_and_saveexec_b64 s[48:49], s[2:3]
	s_cbranch_execz .LBB0_460
	v_add_u32_e32 v1, v125, v123
	s_waitcnt vmcnt(0)
	v_add_u32_e32 v251, 0xf0, v250
	ds_write2_b32 v251, v90, v91 offset1:16
	ds_write2_b32 v251, v92, v93 offset0:32 offset1:48

.LBB0_465:
	s_and_b32 s87, s83, 1
	s_cmp_eq_u32 s87, 0
	s_cselect_b64 s[50:51], -1, 0
	s_and_b64 s[30:31], s[50:51], exec
	s_cselect_b32 s30, 0xf0, s67
	v_and_b32_e32 v98, 63, v154
	v_lshl_add_u32 v98, v98, 2, s30
	ds_read2st64_b32 v[100:101], v98 offset1:1
	ds_read2st64_b32 v[102:103], v98 offset0:2 offset1:3
	ds_read2st64_b32 v[104:105], v98 offset0:4 offset1:5
	ds_read2st64_b32 v[108:109], v98 offset0:8 offset1:9
	s_mov_b64 s[52:53], -1
	s_waitcnt lgkmcnt(3)
	v_mfma_f32_16x16x4_f32 v[94:97], v100, v166, 0
	s_andn2_b64 vcc, exec, s[48:49]
	v_mfma_f32_16x16x4_f32 v[94:97], v101, v165, v[94:97]
	s_waitcnt lgkmcnt(2)
	v_mfma_f32_16x16x4_f32 v[94:97], v102, v164, v[94:97]
	v_mfma_f32_16x16x4_f32 v[94:97], v103, v163, v[94:97]
	s_waitcnt lgkmcnt(1)
	v_mfma_f32_16x16x4_f32 v[100:103], v104, v166, 0
	s_nop 7
	v_add_f32_e32 v94, v162, v94
	v_min_f32_e32 v99, 0, v94
	v_mul_f32_e64 v94, |v94|, s68
	v_exp_f32_e32 v94, v94
	v_add_f32_e32 v95, v162, v95
	v_add_f32_e32 v96, v162, v96
	v_add_f32_e32 v97, v162, v97
	v_add_f32_e32 v94, 1.0, v94
	v_log_f32_e32 v94, v94
	v_mfma_f32_16x16x4_f32 v[100:103], v105, v165, v[100:103]
	ds_read2st64_b32 v[104:105], v98 offset0:6 offset1:7
	v_fmac_f32_e32 v99, 0xbf317218, v94
	v_mul_f32_e32 v94, 0x3d800000, v99
	v_min_f32_e32 v99, 0, v95
	v_mul_f32_e64 v95, |v95|, s68
	v_exp_f32_e32 v95, v95
	s_waitcnt lgkmcnt(0)
	v_mfma_f32_16x16x4_f32 v[100:103], v104, v164, v[100:103]
	v_add_f32_e32 v95, 1.0, v95
	v_log_f32_e32 v95, v95
	s_nop 0
	v_fmac_f32_e32 v99, 0xbf317218, v95
	v_mul_f32_e32 v95, 0x3d800000, v99
	v_min_f32_e32 v99, 0, v96
	v_mul_f32_e64 v96, |v96|, s68
	v_exp_f32_e32 v96, v96
	v_mfma_f32_16x16x4_f32 v[100:103], v105, v163, v[100:103]
	v_add_f32_e32 v96, 1.0, v96
	v_log_f32_e32 v96, v96
	s_nop 0
	v_fmac_f32_e32 v99, 0xbf317218, v96
	v_mul_f32_e32 v96, 0x3d800000, v99
	v_min_f32_e32 v99, 0, v97
	v_mul_f32_e64 v97, |v97|, s68
	v_exp_f32_e32 v97, v97
	v_mfma_f32_16x16x4_f32 v[104:107], v108, v166, 0
	v_add_f32_e32 v97, 1.0, v97
	v_log_f32_e32 v97, v97
	s_nop 0
	v_fmac_f32_e32 v99, 0xbf317218, v97
	v_mul_f32_e32 v97, 0x3d800000, v99
	v_add_f32_e32 v99, v162, v100
	v_min_f32_e32 v100, 0, v99
	v_mul_f32_e64 v99, |v99|, s68
	v_exp_f32_e32 v99, v99
	v_mfma_f32_16x16x4_f32 v[104:107], v109, v165, v[104:107]
	ds_read2st64_b32 v[108:109], v98 offset0:10 offset1:11
	v_add_f32_e32 v99, 1.0, v99
	v_log_f32_e32 v99, v99
	s_nop 0
	v_fmac_f32_e32 v100, 0xbf317218, v99
	v_mul_f32_e32 v99, 0x3d800000, v100
	v_add_f32_e32 v100, v162, v101
	v_min_f32_e32 v101, 0, v100
	v_mul_f32_e64 v100, |v100|, s68
	v_exp_f32_e32 v100, v100
	s_waitcnt lgkmcnt(0)
	v_mfma_f32_16x16x4_f32 v[104:107], v108, v164, v[104:107]
	v_add_f32_e32 v100, 1.0, v100
	v_log_f32_e32 v100, v100
	s_nop 0
	v_fmac_f32_e32 v101, 0xbf317218, v100
	v_mul_f32_e32 v100, 0x3d800000, v101
	v_add_f32_e32 v101, v162, v102
	v_min_f32_e32 v102, 0, v101
	v_mul_f32_e64 v101, |v101|, s68
	v_exp_f32_e32 v101, v101
	v_mfma_f32_16x16x4_f32 v[104:107], v109, v163, v[104:107]
	ds_read2st64_b32 v[108:109], v98 offset0:12 offset1:13
	v_add_f32_e32 v101, 1.0, v101
	v_log_f32_e32 v101, v101
	s_nop 0
	v_fmac_f32_e32 v102, 0xbf317218, v101
	v_mul_f32_e32 v101, 0x3d800000, v102
	v_add_f32_e32 v102, v162, v103
	v_min_f32_e32 v103, 0, v102
	v_mul_f32_e64 v102, |v102|, s68
	v_exp_f32_e32 v102, v102
	s_waitcnt lgkmcnt(0)
	v_mfma_f32_16x16x4_f32 v[168:171], v108, v166, 0
	v_add_f32_e32 v102, 1.0, v102
	v_log_f32_e32 v102, v102
	s_nop 0
	v_fmac_f32_e32 v103, 0xbf317218, v102
	v_mul_f32_e32 v102, 0x3d800000, v103
	v_add_f32_e32 v103, v162, v104
	v_min_f32_e32 v104, 0, v103
	v_mul_f32_e64 v103, |v103|, s68
	v_exp_f32_e32 v103, v103
	v_mfma_f32_16x16x4_f32 v[168:171], v109, v165, v[168:171]
	ds_read2st64_b32 v[108:109], v98 offset0:14 offset1:15
	v_add_f32_e32 v103, 1.0, v103
	v_log_f32_e32 v103, v103
	s_nop 0
	v_fmac_f32_e32 v104, 0xbf317218, v103
	v_mul_f32_e32 v103, 0x3d800000, v104
	v_add_f32_e32 v104, v162, v105
	v_min_f32_e32 v105, 0, v104
	v_mul_f32_e64 v104, |v104|, s68
	v_exp_f32_e32 v104, v104
	s_waitcnt lgkmcnt(0)
	v_mfma_f32_16x16x4_f32 v[168:171], v108, v164, v[168:171]
	v_add_f32_e32 v104, 1.0, v104
	v_log_f32_e32 v104, v104
	s_nop 0
	v_fmac_f32_e32 v105, 0xbf317218, v104
	v_mul_f32_e32 v104, 0x3d800000, v105
	v_add_f32_e32 v105, v162, v106
	v_min_f32_e32 v106, 0, v105
	v_mul_f32_e64 v105, |v105|, s68
	v_exp_f32_e32 v105, v105
	v_mfma_f32_16x16x4_f32 v[168:171], v109, v163, v[168:171]
	v_add_f32_e32 v105, 1.0, v105
	v_log_f32_e32 v105, v105
	s_nop 0
	v_fmac_f32_e32 v106, 0xbf317218, v105
	v_mul_f32_e32 v105, 0x3d800000, v106
	v_add_f32_e32 v106, v162, v107
	v_min_f32_e32 v107, 0, v106
	v_mul_f32_e64 v106, |v106|, s68
	v_exp_f32_e32 v106, v106
	s_nop 0
	v_add_f32_e32 v98, v162, v168
	v_add_f32_e32 v106, 1.0, v106
	v_log_f32_e32 v106, v106
	s_nop 0
	v_fmac_f32_e32 v107, 0xbf317218, v106
	v_mul_f32_e32 v106, 0x3d800000, v107
	v_min_f32_e32 v107, 0, v98
	v_mul_f32_e64 v98, |v98|, s68
	v_exp_f32_e32 v98, v98
	s_nop 0
	v_add_f32_e32 v98, 1.0, v98
	v_log_f32_e32 v98, v98
	s_nop 0
	v_fmac_f32_e32 v107, 0xbf317218, v98
	v_mul_f32_e32 v98, 0x3d800000, v107
	v_add_f32_e32 v107, v162, v169
	v_min_f32_e32 v108, 0, v107
	v_mul_f32_e64 v107, |v107|, s68
	v_exp_f32_e32 v107, v107
	s_nop 0
	v_add_f32_e32 v107, 1.0, v107
	v_log_f32_e32 v107, v107
	s_nop 0
	v_fmac_f32_e32 v108, 0xbf317218, v107
	v_mul_f32_e32 v107, 0x3d800000, v108
	v_add_f32_e32 v108, v162, v170
	v_min_f32_e32 v109, 0, v108
	v_mul_f32_e64 v108, |v108|, s68
	v_exp_f32_e32 v108, v108
	s_nop 0
	v_add_f32_e32 v108, 1.0, v108
	v_log_f32_e32 v108, v108
	s_nop 0
	v_fmac_f32_e32 v109, 0xbf317218, v108
	v_add_f32_e32 v108, v162, v171
	v_mul_f32_e32 v167, 0x3d800000, v109
	v_min_f32_e32 v109, 0, v108
	v_mul_f32_e64 v108, |v108|, s68
	v_exp_f32_e32 v108, v108
	s_nop 0
	v_add_f32_e32 v108, 1.0, v108
	v_log_f32_e32 v108, v108
	s_nop 0
	v_fmac_f32_e32 v109, 0xbf317218, v108
	v_cndmask_b32_e64 v108, 0, 1, s[48:49]
	v_mul_f32_e32 v182, 0x3d800000, v109
	v_cmp_ne_u32_e64 s[30:31], 1, v108
	s_cbranch_vccnz .LBB0_467
	v_add_f32_e32 v108, 0, v182
	v_add_f32_e32 v109, v167, v108
	v_add_f32_e32 v168, v107, v109
	v_add_f32_e32 v169, v98, v168
	v_add_f32_e32 v170, v106, v169
	v_add_f32_e32 v171, v105, v170
	v_add_f32_e32 v172, v104, v171
	v_add_f32_e32 v173, v103, v172
	v_add_f32_e32 v174, v102, v173
	v_add_f32_e32 v175, v101, v174
	v_add_f32_e32 v176, v100, v175
	v_add_f32_e32 v177, v99, v176
	v_add_f32_e32 v178, v97, v177
	v_add_f32_e32 v179, v96, v178
	v_add_f32_e32 v180, v95, v179
	v_add_f32_e32 v181, v94, v180
	s_mov_b64 s[52:53], 0

.LBB0_477:
	s_and_b64 s[50:51], s[50:51], exec
	s_cselect_b32 s50, s67, 0xf0
	v_add_u32_e32 v94, s50, v250
	ds_write2_b32 v94, v90, v91 offset1:16
	ds_write2_b32 v94, v92, v93 offset0:32 offset1:48
	s_or_b64 exec, exec, s[52:53]
	s_cmp_ge_u32 s83, s82
	s_cbranch_scc1 .LBB0_464

.LBB0_480:
	v_and_b32_e32 v108, 63, v154
	v_lshl_add_u32 v108, v108, 2, s67
	ds_read2st64_b32 v[94:95], v108 offset1:1
	ds_read2st64_b32 v[98:99], v108 offset0:2 offset1:3
	ds_read2st64_b32 v[100:101], v108 offset0:4 offset1:5
	ds_read2st64_b32 v[102:103], v108 offset0:6 offset1:7
	s_and_b64 vcc, exec, s[30:31]
	s_mov_b64 s[46:47], -1
	s_waitcnt lgkmcnt(3)
	v_mfma_f32_16x16x4_f32 v[90:93], v94, v166, 0
	v_mfma_f32_16x16x4_f32 v[90:93], v95, v165, v[90:93]
	s_waitcnt lgkmcnt(2)
	v_mfma_f32_16x16x4_f32 v[90:93], v98, v164, v[90:93]
	s_waitcnt lgkmcnt(1)
	v_mfma_f32_16x16x4_f32 v[94:97], v100, v166, 0
	v_mfma_f32_16x16x4_f32 v[90:93], v99, v163, v[90:93]
	s_nop 9
	v_add_f32_e32 v98, v162, v92
	v_add_f32_e32 v99, v162, v93
	v_mfma_f32_16x16x4_f32 v[92:95], v101, v165, v[94:97]
	v_mul_f32_e64 v105, |v98|, s68
	v_exp_f32_e32 v96, v105
	v_add_f32_e32 v91, v162, v91
	v_add_f32_e32 v90, v162, v90
	v_min_f32_e32 v104, 0, v91
	v_add_f32_e32 v96, 1.0, v96
	v_log_f32_e32 v101, v96
	s_waitcnt lgkmcnt(0)
	v_mfma_f32_16x16x4_f32 v[94:97], v102, v164, v[92:95]
	v_mul_f32_e64 v91, |v91|, s68
	v_min_f32_e32 v100, 0, v90
	v_mul_f32_e64 v90, |v90|, s68
	v_exp_f32_e32 v91, v91
	v_mul_f32_e64 v92, |v99|, s68
	v_exp_f32_e32 v90, v90
	v_exp_f32_e32 v93, v92
	v_mfma_f32_16x16x4_f32 v[94:97], v103, v163, v[94:97]
	ds_read2st64_b32 v[102:103], v108 offset0:8 offset1:9
	v_add_f32_e32 v91, 1.0, v91
	v_min_f32_e32 v92, 0, v98
	v_add_f32_e32 v90, 1.0, v90
	v_log_f32_e32 v91, v91
	v_add_f32_e32 v93, 1.0, v93
	v_log_f32_e32 v90, v90
	s_nop 2
	v_add_f32_e32 v94, v162, v94
	v_mul_f32_e64 v98, |v94|, s68
	v_exp_f32_e32 v98, v98
	v_log_f32_e32 v93, v93
	v_fmac_f32_e32 v104, 0xbf317218, v91
	v_min_f32_e32 v99, 0, v99
	v_add_f32_e32 v98, 1.0, v98
	v_add_f32_e32 v95, v162, v95
	v_fmac_f32_e32 v100, 0xbf317218, v90
	v_mul_f32_e32 v91, 0x3d800000, v104
	v_fmac_f32_e32 v99, 0xbf317218, v93
	v_log_f32_e32 v104, v98
	v_mul_f32_e64 v98, |v95|, s68
	v_mul_f32_e32 v90, 0x3d800000, v100
	v_fmac_f32_e32 v92, 0xbf317218, v101
	v_mul_f32_e32 v93, 0x3d800000, v99
	v_exp_f32_e32 v105, v98
	s_waitcnt lgkmcnt(0)
	v_mfma_f32_16x16x4_f32 v[98:101], v102, v166, 0
	v_min_f32_e32 v94, 0, v94
	v_fmac_f32_e32 v94, 0xbf317218, v104
	v_add_f32_e32 v102, 1.0, v105
	ds_read2st64_b32 v[104:105], v108 offset0:10 offset1:11
	v_add_f32_e32 v106, v162, v96
	v_mul_f32_e64 v96, |v106|, s68
	v_exp_f32_e32 v96, v96
	v_mfma_f32_16x16x4_f32 v[98:101], v103, v165, v[98:101]
	v_log_f32_e32 v102, v102
	v_min_f32_e32 v95, 0, v95
	v_add_f32_e32 v96, 1.0, v96
	v_add_f32_e32 v103, v162, v97
	v_fmac_f32_e32 v95, 0xbf317218, v102
	v_log_f32_e32 v102, v96
	v_mul_f32_e32 v92, 0x3d800000, v92
	s_waitcnt lgkmcnt(0)
	v_mfma_f32_16x16x4_f32 v[96:99], v104, v164, v[98:101]
	s_nop 0
	v_mul_f32_e64 v100, |v103|, s68
	v_exp_f32_e32 v100, v100
	v_min_f32_e32 v104, 0, v106
	v_fmac_f32_e32 v104, 0xbf317218, v102
	ds_read2st64_b32 v[106:107], v108 offset0:12 offset1:13
	v_add_f32_e32 v100, 1.0, v100
	v_log_f32_e32 v102, v100
	v_mfma_f32_16x16x4_f32 v[98:101], v105, v163, v[96:99]
	v_min_f32_e32 v103, 0, v103
	v_mul_f32_e32 v94, 0x3d800000, v94
	v_fmac_f32_e32 v103, 0xbf317218, v102
	v_mul_f32_e32 v95, 0x3d800000, v95
	s_nop 5
	v_add_f32_e32 v98, v162, v98
	v_mul_f32_e64 v96, |v98|, s68
	v_exp_f32_e32 v97, v96
	v_add_f32_e32 v99, v162, v99
	v_mul_f32_e32 v96, 0x3d800000, v104
	v_min_f32_e32 v98, 0, v98
	v_add_f32_e32 v97, 1.0, v97
	v_log_f32_e32 v102, v97
	v_mul_f32_e64 v97, |v99|, s68
	v_exp_f32_e32 v104, v97
	v_mul_f32_e32 v97, 0x3d800000, v103
	v_fmac_f32_e32 v98, 0xbf317218, v102
	v_min_f32_e32 v99, 0, v99
	v_add_f32_e32 v102, 1.0, v104
	v_log_f32_e32 v109, v102
	s_waitcnt lgkmcnt(0)
	v_mfma_f32_16x16x4_f32 v[102:105], v106, v166, 0
	v_add_f32_e32 v100, v162, v100
	v_min_f32_e32 v106, 0, v100
	v_fmac_f32_e32 v99, 0xbf317218, v109
	ds_read2st64_b32 v[108:109], v108 offset0:14 offset1:15
	v_mul_f32_e64 v100, |v100|, s68
	v_exp_f32_e32 v100, v100
	v_mul_f32_e32 v98, 0x3d800000, v98
	v_mfma_f32_16x16x4_f32 v[102:105], v107, v165, v[102:105]
	v_add_f32_e32 v107, v162, v101
	v_mul_f32_e64 v101, |v107|, s68
	v_add_f32_e32 v100, 1.0, v100
	v_exp_f32_e32 v165, v101
	v_log_f32_e32 v166, v100
	v_mul_f32_e32 v99, 0x3d800000, v99
	v_fmac_f32_e32 v106, 0xbf317218, v166
	s_waitcnt lgkmcnt(0)
	v_mfma_f32_16x16x4_f32 v[100:103], v108, v164, v[102:105]
	s_nop 0
	v_add_f32_e32 v104, 1.0, v165
	v_log_f32_e32 v104, v104
	v_min_f32_e32 v105, 0, v107
	v_mul_f32_e32 v168, 0x3d800000, v106
	v_fmac_f32_e32 v105, 0xbf317218, v104
	v_mul_f32_e32 v169, 0x3d800000, v105
	v_mfma_f32_16x16x4_f32 v[100:103], v109, v163, v[100:103]
	s_nop 9
	v_add_f32_e32 v100, v162, v100
	v_mul_f32_e64 v104, |v100|, s68
	v_exp_f32_e32 v104, v104
	v_add_f32_e32 v101, v162, v101
	v_mul_f32_e64 v105, |v101|, s68
	v_exp_f32_e32 v105, v105
	v_add_f32_e32 v104, 1.0, v104
	v_log_f32_e32 v104, v104
	v_min_f32_e32 v100, 0, v100
	v_add_f32_e32 v105, 1.0, v105
	v_log_f32_e32 v105, v105
	v_fmac_f32_e32 v100, 0xbf317218, v104
	v_mul_f32_e32 v170, 0x3d800000, v100
	v_min_f32_e32 v100, 0, v101
	v_fmac_f32_e32 v100, 0xbf317218, v105
	v_mul_f32_e32 v171, 0x3d800000, v100
	v_add_f32_e32 v100, v162, v102
	v_mul_f32_e64 v101, |v100|, s68
	v_exp_f32_e32 v101, v101
	v_add_f32_e32 v102, v162, v103
	v_mul_f32_e64 v103, |v102|, s68
	v_exp_f32_e32 v103, v103
	v_add_f32_e32 v101, 1.0, v101
	v_log_f32_e32 v101, v101
	v_min_f32_e32 v100, 0, v100
	v_add_f32_e32 v103, 1.0, v103
	v_log_f32_e32 v103, v103
	v_fmac_f32_e32 v100, 0xbf317218, v101
	v_mul_f32_e32 v172, 0x3d800000, v100
	v_min_f32_e32 v100, 0, v102
	v_fmac_f32_e32 v100, 0xbf317218, v103
	v_mul_f32_e32 v173, 0x3d800000, v100
	s_cbranch_vccnz .LBB0_482
	v_add_f32_e32 v100, 0, v173
	v_add_f32_e32 v101, v172, v100
	v_add_f32_e32 v102, v171, v101
	v_add_f32_e32 v103, v170, v102
	v_add_f32_e32 v104, v169, v103
	v_add_f32_e32 v105, v168, v104
	v_add_f32_e32 v106, v99, v105
	v_add_f32_e32 v107, v98, v106
	v_add_f32_e32 v108, v97, v107
	v_add_f32_e32 v109, v96, v108
	v_add_f32_e32 v162, v95, v109
	v_add_f32_e32 v163, v94, v162
	v_add_f32_e32 v164, v93, v163
	v_add_f32_e32 v165, v92, v164
	v_add_f32_e32 v166, v91, v165
	v_add_f32_e32 v167, v90, v166
	s_mov_b64 s[46:47], 0

.LBB0_495:
	s_or_b64 exec, exec, s[48:49]
	s_and_saveexec_b64 s[44:45], s[2:3]
	s_cbranch_execz .LBB0_497
	v_add_u32_e32 v1, v125, v123
	s_waitcnt vmcnt(0)
	v_add_u32_e32 v251, 0xf0, v250
	ds_write2_b32 v251, v2, v3 offset1:16
	ds_write2_b32 v251, v4, v5 offset0:32 offset1:48

.LBB0_502:
	s_add_u32 s50, s53, s46
	s_addc_u32 s51, s77, s47
	s_add_u32 s31, s43, s46
	s_addc_u32 s48, s52, s47
	s_add_u32 s80, s31, s76
	s_addc_u32 s81, s48, 0
	s_and_b32 s79, s78, 1
	s_cmp_eq_u32 s79, 0
	s_cselect_b64 s[48:49], -1, 0
	s_and_b64 s[82:83], s[48:49], exec
	s_cselect_b32 s31, 0xf0, s67
	v_and_b32_e32 v1, 63, v154
	v_lshl_add_u32 v1, v1, 2, s31
	ds_read2st64_b32 v[74:75], v1 offset1:1
	v_lshl_add_u64 v[76:77], s[50:51], 0, v[112:113]
	ds_read2st64_b32 v[82:83], v1 offset0:4 offset1:5
	global_load_dwordx4 v[94:97], v[76:77], off
	global_load_dwordx4 v[98:101], v[76:77], off offset:1024
	ds_read2st64_b32 v[108:109], v1 offset0:2 offset1:3
	v_lshl_add_u64 v[84:85], s[80:81], 0, v[114:115]
	s_mov_b32 s31, 0x3d800000
	s_waitcnt vmcnt(6) lgkmcnt(2)
	v_mfma_f32_16x16x4_f32 v[70:73], v74, v102, 0
	v_add_co_u32_e32 v74, vcc, s63, v76
	s_waitcnt vmcnt(5)
	v_mfma_f32_16x16x4_f32 v[70:73], v75, v103, v[70:73]
	v_addc_co_u32_e32 v75, vcc, 0, v77, vcc
	global_load_dwordx4 v[86:89], v[74:75], off
	global_load_dwordx4 v[90:93], v[74:75], off offset:1024
	v_add_co_u32_e32 v74, vcc, s64, v84
	s_nop 1
	v_addc_co_u32_e32 v75, vcc, 0, v85, vcc
	s_waitcnt vmcnt(6) lgkmcnt(0)
	v_mfma_f32_16x16x4_f32 v[160:163], v108, v104, v[70:73]
	v_add_co_u32_e32 v168, vcc, s63, v84
	global_load_dwordx4 v[70:73], v[84:85], off
	s_nop 0
	global_load_dwordx4 v[74:77], v[74:75], off
	v_addc_co_u32_e32 v169, vcc, 0, v85, vcc
	v_mfma_f32_16x16x4_f32 v[78:81], v82, v102, 0
	v_add_co_u32_e32 v82, vcc, s65, v84
	s_waitcnt vmcnt(7)
	v_mfma_f32_16x16x4_f32 v[160:163], v109, v105, v[160:163]
	v_mfma_f32_16x16x4_f32 v[164:167], v83, v103, v[78:81]
	v_addc_co_u32_e32 v83, vcc, 0, v85, vcc
	s_nop 4
	global_load_dwordx4 v[78:81], v[168:169], off
	s_nop 0
	global_load_dwordx4 v[82:85], v[82:83], off
	ds_read2st64_b32 v[168:169], v1 offset0:6 offset1:7
	s_waitcnt vmcnt(8)
	v_add_f32_e32 v107, v106, v160
	v_min_f32_e32 v170, 0, v107
	v_mul_f32_e64 v107, |v107|, s68
	v_exp_f32_e32 v107, v107
	v_add_f32_e32 v108, v106, v161
	v_add_f32_e32 v109, v106, v162
	v_mul_f32_e64 v160, |v108|, s68
	v_mul_f32_e64 v161, |v109|, s68
	v_exp_f32_e32 v160, v160
	v_exp_f32_e32 v161, v161
	v_add_f32_e32 v107, 1.0, v107
	v_log_f32_e32 v107, v107
	s_waitcnt lgkmcnt(0)
	v_mfma_f32_16x16x4_f32 v[164:167], v168, v104, v[164:167]
	v_add_f32_e32 v160, 1.0, v160
	v_add_f32_e32 v161, 1.0, v161
	v_log_f32_e32 v160, v160
	v_fmac_f32_e32 v170, 0xbf317218, v107
	v_log_f32_e32 v107, v161
	v_min_f32_e32 v171, 0, v108
	v_min_f32_e32 v172, 0, v109
	v_fmac_f32_e32 v171, 0xbf317218, v160
	v_fmac_f32_e32 v172, 0xbf317218, v107
	v_add_f32_e32 v107, v106, v163
	v_mfma_f32_16x16x4_f32 v[160:163], v169, v105, v[164:167]
	v_mul_f32_e64 v108, |v107|, s68
	v_exp_f32_e32 v168, v108
	v_min_f32_e32 v107, 0, v107
	v_add_f32_e32 v165, 1.0, v168
	v_log_f32_e32 v165, v165
	s_nop 4
	v_add_f32_e32 v160, v106, v160
	v_mul_f32_e64 v108, |v160|, s68
	v_exp_f32_e32 v164, v108
	ds_read2st64_b32 v[108:109], v1 offset0:8 offset1:9
	v_min_f32_e32 v173, 0, v160
	v_fmac_f32_e32 v107, 0xbf317218, v165
	v_add_f32_e32 v164, 1.0, v164
	v_log_f32_e32 v164, v164
	ds_read2st64_b32 v[168:169], v1 offset0:10 offset1:11
	v_add_f32_e32 v174, v106, v162
	v_add_f32_e32 v176, v106, v163
	v_fmac_f32_e32 v173, 0xbf317218, v164
	s_waitcnt lgkmcnt(1)
	v_mfma_f32_16x16x4_f32 v[164:167], v108, v102, 0
	v_add_f32_e32 v108, v106, v161
	v_mul_f32_e64 v160, |v108|, s68
	v_mul_f32_e64 v161, |v174|, s68
	v_exp_f32_e32 v160, v160
	v_exp_f32_e32 v161, v161
	v_min_f32_e32 v175, 0, v108
	v_mul_f32_e64 v177, |v176|, s68
	v_mfma_f32_16x16x4_f32 v[164:167], v109, v103, v[164:167]
	v_add_f32_e32 v108, 1.0, v160
	v_add_f32_e32 v109, 1.0, v161
	v_log_f32_e32 v108, v108
	v_log_f32_e32 v109, v109
	v_min_f32_e32 v174, 0, v174
	v_min_f32_e32 v176, 0, v176
	v_fmac_f32_e32 v175, 0xbf317218, v108
	s_waitcnt lgkmcnt(0)
	v_mfma_f32_16x16x4_f32 v[160:163], v168, v104, v[164:167]
	s_nop 0
	v_exp_f32_e32 v164, v177
	v_fmac_f32_e32 v174, 0xbf317218, v109
	v_add_f32_e32 v108, 1.0, v164
	v_log_f32_e32 v164, v108
	ds_read2st64_b32 v[108:109], v1 offset0:12 offset1:13
	v_mfma_f32_16x16x4_f32 v[160:163], v169, v105, v[160:163]
	v_fmac_f32_e32 v176, 0xbf317218, v164
	s_nop 8
	v_add_f32_e32 v160, v106, v160
	v_mul_f32_e64 v164, |v160|, s68
	v_exp_f32_e32 v168, v164
	s_waitcnt lgkmcnt(0)
	v_mfma_f32_16x16x4_f32 v[164:167], v108, v102, 0
	v_add_f32_e32 v161, v106, v161
	v_mul_f32_e64 v169, |v161|, s68
	v_exp_f32_e32 v108, v169
	v_min_f32_e32 v177, 0, v160
	v_add_f32_e32 v160, 1.0, v168
	ds_read2st64_b32 v[168:169], v1 offset0:14 offset1:15
	v_add_f32_e32 v108, 1.0, v108
	v_mfma_f32_16x16x4_f32 v[164:167], v109, v103, v[164:167]
	v_log_f32_e32 v160, v160
	v_log_f32_e32 v108, v108
	v_min_f32_e32 v1, 0, v161
	v_add_f32_e32 v178, v106, v163
	v_fmac_f32_e32 v177, 0xbf317218, v160
	v_fmac_f32_e32 v1, 0xbf317218, v108
	v_add_f32_e32 v108, v106, v162
	s_waitcnt lgkmcnt(0)
	v_mfma_f32_16x16x4_f32 v[160:163], v168, v104, v[164:167]
	v_mul_f32_e64 v109, |v108|, s68
	v_exp_f32_e32 v109, v109
	v_mul_f32_e64 v164, |v178|, s68
	v_exp_f32_e32 v164, v164
	v_min_f32_e32 v108, 0, v108
	v_add_f32_e32 v109, 1.0, v109
	v_log_f32_e32 v109, v109
	v_mfma_f32_16x16x4_f32 v[160:163], v169, v105, v[160:163]
	v_add_f32_e32 v164, 1.0, v164
	v_log_f32_e32 v164, v164
	v_fmac_f32_e32 v108, 0xbf317218, v109
	v_min_f32_e32 v109, 0, v178
	v_fmac_f32_e32 v109, 0xbf317218, v164
	s_nop 4
	v_add_f32_e32 v160, v106, v160
	v_mul_f32_e64 v165, |v160|, s68
	v_exp_f32_e32 v165, v165
	v_add_f32_e32 v161, v106, v161
	v_min_f32_e32 v160, 0, v160
	v_add_f32_e32 v162, v106, v162
	v_add_f32_e32 v164, 1.0, v165
	v_mul_f32_e64 v165, |v161|, s68
	v_log_f32_e32 v164, v164
	v_exp_f32_e32 v165, v165
	v_add_f32_e32 v163, v106, v163
	v_mul_f32_e64 v166, |v163|, s68
	v_fmac_f32_e32 v160, 0xbf317218, v164
	v_add_f32_e32 v164, 1.0, v165
	v_mul_f32_e64 v165, |v162|, s68
	v_log_f32_e32 v164, v164
	v_exp_f32_e32 v165, v165
	v_exp_f32_e32 v166, v166
	v_min_f32_e32 v161, 0, v161
	v_fmac_f32_e32 v161, 0xbf317218, v164
	v_add_f32_e32 v164, 1.0, v165
	v_log_f32_e32 v164, v164
	v_add_f32_e32 v165, 1.0, v166
	v_log_f32_e32 v165, v165
	v_min_f32_e32 v162, 0, v162
	v_fmac_f32_e32 v162, 0xbf317218, v164
	v_min_f32_e32 v163, 0, v163
	v_fma_f32 v164, v170, s31, 0
	v_fmac_f32_e32 v163, 0xbf317218, v165
	v_fmamk_f32 v165, v171, 0x3d800000, v164
	v_fmamk_f32 v166, v172, 0x3d800000, v165
	v_fmamk_f32 v107, v107, 0x3d800000, v166
	v_fmamk_f32 v167, v173, 0x3d800000, v107
	v_fmamk_f32 v168, v175, 0x3d800000, v167
	v_fmamk_f32 v169, v174, 0x3d800000, v168
	v_fmamk_f32 v170, v176, 0x3d800000, v169
	v_fmamk_f32 v171, v177, 0x3d800000, v170
	v_fmamk_f32 v1, v1, 0x3d800000, v171
	v_fmamk_f32 v108, v108, 0x3d800000, v1
	v_fmamk_f32 v109, v109, 0x3d800000, v108
	v_fmamk_f32 v160, v160, 0x3d800000, v109
	v_fmamk_f32 v161, v161, 0x3d800000, v160
	v_fmamk_f32 v162, v162, 0x3d800000, v161
	v_fmamk_f32 v163, v163, 0x3d800000, v162
	ds_bpermute_b32 v172, v137, v163
	ds_bpermute_b32 v173, v138, v163
	ds_bpermute_b32 v174, v139, v163
	s_waitcnt lgkmcnt(2)
	v_cndmask_b32_e64 v172, v172, 0, s[10:11]
	s_waitcnt lgkmcnt(1)
	v_cndmask_b32_e64 v173, 0, v173, s[12:13]
	v_add_f32_e32 v172, v172, v173
	s_waitcnt lgkmcnt(0)
	v_cndmask_b32_e64 v173, 0, v174, s[6:7]
	v_add_f32_e32 v172, v172, v173
	v_add_f32_e32 v164, v164, v172
	v_add_f32_e32 v165, v165, v172
	ds_write2st64_b32 v141, v164, v165 offset0:24 offset1:26
	v_add_f32_e32 v164, v166, v172
	v_add_f32_e32 v107, v107, v172
	ds_write2st64_b32 v141, v164, v107 offset0:28 offset1:30
	v_add_f32_e32 v107, v167, v172
	v_add_f32_e32 v164, v168, v172
	ds_write2st64_b32 v141, v107, v164 offset0:32 offset1:34
	v_add_f32_e32 v107, v169, v172
	v_add_f32_e32 v164, v170, v172
	ds_write2st64_b32 v141, v107, v164 offset0:36 offset1:38
	v_add_f32_e32 v107, v171, v172
	v_add_f32_e32 v1, v1, v172
	ds_write2st64_b32 v141, v107, v1 offset0:40 offset1:42
	v_add_f32_e32 v1, v172, v108
	v_add_f32_e32 v107, v172, v109
	ds_write2st64_b32 v141, v1, v107 offset0:44 offset1:46
	v_add_f32_e32 v1, v172, v160
	v_add_f32_e32 v107, v172, v161
	ds_write2st64_b32 v141, v1, v107 offset0:48 offset1:50
	v_add_f32_e32 v1, v172, v162
	v_add_f32_e32 v107, v172, v163
	ds_write2st64_b32 v141, v1, v107 offset0:52 offset1:54
	s_waitcnt lgkmcnt(0)
	s_barrier
	s_and_saveexec_b64 s[50:51], s[4:5]
	s_cbranch_execz .LBB0_504
	ds_read_b32 v1, v127 offset:38400
	v_lshl_add_u32 v107, s79, 9, v127
	s_waitcnt lgkmcnt(0)
	ds_write_b32 v107, v1 offset:4096
.LBB0_504:
	s_or_b64 exec, exec, s[50:51]
	s_cmp_gt_u32 s78, 2
	s_cbranch_scc1 .LBB0_501
	s_and_saveexec_b64 s[50:51], s[2:3]
	s_and_b64 s[48:49], s[48:49], exec
	s_cselect_b32 s31, s67, 0xf0
	v_add_u32_e32 v1, s31, v250
	ds_write2_b32 v1, v2, v3 offset1:16
	ds_write2_b32 v1, v4, v5 offset0:32 offset1:48
	s_or_b64 exec, exec, s[50:51]
	s_cmp_eq_u32 s46, 0xc0000
	s_cbranch_scc1 .LBB0_501
	s_ashr_i32 s31, s30, 31
	s_lshl_b64 s[48:49], s[30:31], 7
	s_add_u32 s50, s41, s48
	s_addc_u32 s51, s54, s49
	s_and_saveexec_b64 s[48:49], s[2:3]
	s_cbranch_execz .LBB0_500
	v_lshl_add_u64 v[2:3], s[50:51], 0, v[110:111]
	global_load_dwordx4 v[2:5], v[2:3], off
	s_branch .LBB0_500

.LBB0_566:
	v_lshrrev_b32_e32 v250, 6, v154
	v_bfe_u32 v251, v154, 2, 2
	v_lshlrev_b32_e32 v250, 4, v250
	v_lshl_add_u32 v250, v251, 2, v250
	v_and_b32_e32 v251, 3, v154
	v_lshl_add_u32 v250, v251, 8, v250
	v_bfe_u32 v251, v154, 4, 2
	v_lshl_add_u32 v250, v251, 10, v250
	v_mov_b32_e32 v4, 0
	ds_read_b128 v[0:3], v4 offset:80
	ds_read2_b64 v[4:7], v4 offset0:12 offset1:27
	v_readlane_b32 s4, v240, 0
	s_cmp_gt_i32 s4, 15
	s_mov_b64 s[4:5], -1
	s_waitcnt lgkmcnt(0)
	v_readfirstlane_b32 s3, v1
	v_readfirstlane_b32 s2, v0
	v_readfirstlane_b32 s1, v3
	v_readfirstlane_b32 s0, v2
	v_readfirstlane_b32 s28, v5
	v_readfirstlane_b32 s30, v4
	v_readfirstlane_b32 s41, v7
	v_readfirstlane_b32 s43, v6
	s_cbranch_scc0 .LBB0_571
	v_readlane_b32 s4, v240, 0
	s_mov_b32 s12, 0x40000
	s_nop 0
	v_lshl_add_u32 v0, s4, 9, v154
	v_add_u32_e32 v2, 0xffffe000, v0
	v_cmp_gt_u32_e32 vcc, s12, v2
	s_and_saveexec_b64 s[4:5], vcc
	s_cbranch_execz .LBB0_570
	s_add_u32 s6, s43, 0x6b20000
	s_addc_u32 s7, s41, 0
	s_add_u32 s8, s43, 0xab20000
	s_addc_u32 s9, s41, 0
	s_lshl_b32 s13, s66, 9
	s_addk_i32 s13, 0xe000
	s_mov_b64 s[10:11], 0
	v_mov_b32_e32 v1, 0
	s_movk_i32 s14, 0x1000
	s_mov_b32 s15, 0x3ffff

.LBB0_574:
	s_or_b64 exec, exec, s[4:5]
	v_lshlrev_b32_e32 v169, 6, v9
	s_and_saveexec_b64 s[2:3], vcc
	s_cbranch_execz .LBB0_576
	s_movk_i32 s4, 0xf0
	v_add_u32_e32 v9, s4, v250
	s_waitcnt vmcnt(0)
	ds_write2_b32 v9, v0, v1 offset1:16
	ds_write2_b32 v9, v2, v3 offset0:32 offset1:48

.LBB0_580:
	s_add_u32 s0, s50, s38
	s_addc_u32 s1, s51, s39
	s_add_u32 s60, s48, s38
	s_addc_u32 s61, s49, s39
	s_add_u32 s31, s60, s46
	s_addc_u32 s44, s61, 0
	s_add_u32 s62, s31, 0x16e40800
	s_addc_u32 s63, s44, 0
	s_and_b32 s59, s58, 1
	s_cmp_eq_u32 s59, 0
	s_cselect_b64 s[44:45], -1, 0
	s_and_b64 s[64:65], s[44:45], exec
	s_cselect_b32 s31, 0xf0, s54
	v_and_b32_e32 v136, 63, v154
	v_lshl_add_u32 v136, v136, 2, s31
	ds_read2st64_b32 v[72:73], v136 offset1:1
	v_lshl_add_u64 v[74:75], s[0:1], 0, v[102:103]
	ds_read2st64_b32 v[80:81], v136 offset0:4 offset1:5
	global_load_dwordx4 v[92:95], v[74:75], off
	global_load_dwordx4 v[96:99], v[74:75], off offset:1024
	ds_read2st64_b32 v[132:133], v136 offset0:2 offset1:3
	v_lshl_add_u64 v[82:83], s[62:63], 0, v[104:105]
	s_waitcnt lgkmcnt(2)
	v_mfma_f32_16x16x4_f32 v[68:71], v72, v155, 0
	v_add_co_u32_e64 v72, s[0:1], s52, v74
	v_mfma_f32_16x16x4_f32 v[68:71], v73, v164, v[68:71]
	s_nop 0
	v_addc_co_u32_e64 v73, s[0:1], 0, v75, s[0:1]
	global_load_dwordx4 v[84:87], v[72:73], off
	global_load_dwordx4 v[88:91], v[72:73], off offset:1024
	v_add_co_u32_e64 v72, s[0:1], s47, v82
	s_nop 1
	v_addc_co_u32_e64 v73, s[0:1], 0, v83, s[0:1]
	s_waitcnt lgkmcnt(0)
	v_mfma_f32_16x16x4_f32 v[124:127], v132, v165, v[68:71]
	v_add_co_u32_e64 v134, s[0:1], s52, v82
	global_load_dwordx4 v[68:71], v[82:83], off
	s_nop 0
	global_load_dwordx4 v[72:75], v[72:73], off
	v_addc_co_u32_e64 v135, s[0:1], 0, v83, s[0:1]
	v_mfma_f32_16x16x4_f32 v[76:79], v80, v155, 0
	v_add_co_u32_e64 v80, s[0:1], s53, v82
	v_mfma_f32_16x16x4_f32 v[124:127], v133, v166, v[124:127]
	v_mfma_f32_16x16x4_f32 v[128:131], v81, v164, v[76:79]
	v_addc_co_u32_e64 v81, s[0:1], 0, v83, s[0:1]
	s_nop 5
	global_load_dwordx4 v[76:79], v[134:135], off
	s_nop 0
	global_load_dwordx4 v[80:83], v[80:81], off
	ds_read2st64_b32 v[134:135], v136 offset0:6 offset1:7
	v_add_f32_e32 v124, v167, v124
	v_min_f32_e32 v137, 0, v124
	v_mul_f32_e64 v124, |v124|, s55
	v_exp_f32_e32 v124, v124
	v_add_f32_e32 v126, v167, v126
	v_mul_f32_e64 v133, |v126|, s55
	v_exp_f32_e32 v133, v133
	v_add_f32_e32 v124, 1.0, v124
	v_log_f32_e32 v124, v124
	s_waitcnt lgkmcnt(0)
	v_mfma_f32_16x16x4_f32 v[128:131], v134, v165, v[128:131]
	v_add_f32_e32 v133, 1.0, v133
	v_min_f32_e32 v139, 0, v126
	v_fmac_f32_e32 v137, 0xbf317218, v124
	v_log_f32_e32 v124, v133
	v_add_f32_e32 v134, v167, v127
	v_add_f32_e32 v125, v167, v125
	v_mul_f32_e64 v132, |v125|, s55
	v_fmac_f32_e32 v139, 0xbf317218, v124
	v_mul_f32_e64 v124, |v134|, s55
	v_min_f32_e32 v138, 0, v125
	v_exp_f32_e32 v140, v124
	v_mfma_f32_16x16x4_f32 v[124:127], v135, v166, v[128:131]
	v_exp_f32_e32 v132, v132
	v_add_f32_e32 v129, 1.0, v140
	v_log_f32_e32 v129, v129
	v_add_f32_e32 v132, 1.0, v132
	v_log_f32_e32 v132, v132
	v_min_f32_e32 v140, 0, v134
	s_nop 3
	v_add_f32_e32 v124, v167, v124
	v_mul_f32_e64 v128, |v124|, s55
	v_fmac_f32_e32 v138, 0xbf317218, v132
	v_exp_f32_e32 v128, v128
	ds_read2st64_b32 v[132:133], v136 offset0:8 offset1:9
	v_min_f32_e32 v141, 0, v124
	v_fmac_f32_e32 v140, 0xbf317218, v129
	v_add_f32_e32 v128, 1.0, v128
	v_log_f32_e32 v128, v128
	ds_read2st64_b32 v[134:135], v136 offset0:10 offset1:11
	v_add_f32_e32 v124, v167, v125
	v_mul_f32_e64 v125, |v124|, s55
	v_fmac_f32_e32 v141, 0xbf317218, v128
	s_waitcnt lgkmcnt(1)
	v_mfma_f32_16x16x4_f32 v[128:131], v132, v155, 0
	v_add_f32_e32 v132, v167, v126
	v_exp_f32_e32 v125, v125
	v_mul_f32_e64 v126, |v132|, s55
	v_exp_f32_e32 v126, v126
	v_min_f32_e32 v142, 0, v124
	v_add_f32_e32 v124, 1.0, v125
	v_add_f32_e32 v144, v167, v127
	v_mfma_f32_16x16x4_f32 v[128:131], v133, v164, v[128:131]
	v_log_f32_e32 v133, v124
	v_add_f32_e32 v124, 1.0, v126
	v_log_f32_e32 v143, v124
	v_mul_f32_e64 v145, |v144|, s55
	v_fmac_f32_e32 v142, 0xbf317218, v133
	s_waitcnt lgkmcnt(0)
	v_mfma_f32_16x16x4_f32 v[124:127], v134, v165, v[128:131]
	s_nop 2
	v_exp_f32_e32 v128, v145
	v_min_f32_e32 v145, 0, v132
	ds_read2st64_b32 v[132:133], v136 offset0:12 offset1:13
	v_fmac_f32_e32 v145, 0xbf317218, v143
	v_add_f32_e32 v128, 1.0, v128
	v_log_f32_e32 v128, v128
	v_min_f32_e32 v143, 0, v144
	v_mfma_f32_16x16x4_f32 v[124:127], v135, v166, v[124:127]
	v_fmac_f32_e32 v143, 0xbf317218, v128
	s_nop 8
	v_add_f32_e32 v124, v167, v124
	v_mul_f32_e64 v128, |v124|, s55
	v_exp_f32_e32 v134, v128
	s_waitcnt lgkmcnt(0)
	v_mfma_f32_16x16x4_f32 v[128:131], v132, v155, 0
	v_add_f32_e32 v125, v167, v125
	v_mul_f32_e64 v135, |v125|, s55
	v_exp_f32_e32 v132, v135
	v_min_f32_e32 v144, 0, v124
	v_add_f32_e32 v124, 1.0, v134
	ds_read2st64_b32 v[134:135], v136 offset0:14 offset1:15
	v_add_f32_e32 v132, 1.0, v132
	v_mfma_f32_16x16x4_f32 v[128:131], v133, v164, v[128:131]
	v_log_f32_e32 v132, v132
	v_log_f32_e32 v124, v124
	v_min_f32_e32 v133, 0, v125
	v_add_f32_e32 v146, v167, v127
	v_fmac_f32_e32 v133, 0xbf317218, v132
	v_add_f32_e32 v132, v167, v126
	v_fmac_f32_e32 v144, 0xbf317218, v124
	v_mul_f32_e64 v124, |v132|, s55
	v_exp_f32_e32 v136, v124
	s_waitcnt lgkmcnt(0)
	v_mfma_f32_16x16x4_f32 v[124:127], v134, v165, v[128:131]
	v_mul_f32_e64 v128, |v146|, s55
	v_exp_f32_e32 v128, v128
	v_add_f32_e32 v130, 1.0, v136
	v_log_f32_e32 v130, v130
	v_min_f32_e32 v129, 0, v132
	v_add_f32_e32 v128, 1.0, v128
	v_log_f32_e32 v128, v128
	v_mfma_f32_16x16x4_f32 v[124:127], v135, v166, v[124:127]
	v_fmac_f32_e32 v129, 0xbf317218, v130
	v_min_f32_e32 v130, 0, v146
	v_fmac_f32_e32 v130, 0xbf317218, v128
	s_nop 6
	v_add_f32_e32 v124, v167, v124
	v_mul_f32_e64 v131, |v124|, s55
	v_exp_f32_e32 v131, v131
	v_add_f32_e32 v125, v167, v125
	v_min_f32_e32 v124, 0, v124
	v_add_f32_e32 v126, v167, v126
	v_add_f32_e32 v128, 1.0, v131
	v_mul_f32_e64 v131, |v125|, s55
	v_log_f32_e32 v128, v128
	v_exp_f32_e32 v131, v131
	v_add_f32_e32 v127, v167, v127
	v_mul_f32_e64 v132, |v127|, s55
	v_fmac_f32_e32 v124, 0xbf317218, v128
	v_add_f32_e32 v128, 1.0, v131
	v_mul_f32_e64 v131, |v126|, s55
	v_log_f32_e32 v128, v128
	v_exp_f32_e32 v131, v131
	v_exp_f32_e32 v132, v132
	v_min_f32_e32 v125, 0, v125
	v_fmac_f32_e32 v125, 0xbf317218, v128
	v_add_f32_e32 v128, 1.0, v131
	v_add_f32_e32 v131, 1.0, v132
	v_log_f32_e32 v131, v131
	v_log_f32_e32 v128, v128
	v_min_f32_e32 v127, 0, v127
	v_min_f32_e32 v126, 0, v126
	v_fmac_f32_e32 v127, 0xbf317218, v131
	v_fmac_f32_e32 v126, 0xbf317218, v128
	v_fma_f32 v127, v127, s56, 0
	v_fmamk_f32 v126, v126, 0x3d800000, v127
	v_fmamk_f32 v125, v125, 0x3d800000, v126
	v_fmamk_f32 v124, v124, 0x3d800000, v125
	v_fmamk_f32 v128, v130, 0x3d800000, v124
	v_fmamk_f32 v129, v129, 0x3d800000, v128
	v_fmamk_f32 v130, v133, 0x3d800000, v129
	v_fmamk_f32 v131, v144, 0x3d800000, v130
	v_fmamk_f32 v132, v143, 0x3d800000, v131
	v_fmamk_f32 v133, v145, 0x3d800000, v132
	v_fmamk_f32 v134, v142, 0x3d800000, v133
	v_fmamk_f32 v135, v141, 0x3d800000, v134
	v_fmamk_f32 v136, v140, 0x3d800000, v135
	v_fmamk_f32 v139, v139, 0x3d800000, v136
	v_fmamk_f32 v138, v138, 0x3d800000, v139
	v_fmamk_f32 v137, v137, 0x3d800000, v138
	ds_bpermute_b32 v140, v174, v137
	ds_bpermute_b32 v141, v173, v137
	ds_bpermute_b32 v142, v172, v137
	s_waitcnt lgkmcnt(2)
	v_cndmask_b32_e64 v140, v140, 0, s[2:3]
	s_waitcnt lgkmcnt(1)
	v_cndmask_b32_e64 v141, 0, v141, s[4:5]
	v_add_f32_e32 v140, v141, v140
	s_waitcnt lgkmcnt(0)
	v_cndmask_b32_e64 v141, 0, v142, s[6:7]
	v_add_f32_e32 v140, v141, v140
	v_add_f32_e32 v137, v140, v137
	v_add_f32_e32 v138, v140, v138
	v_add_f32_e32 v124, v140, v124
	v_add_f32_e32 v125, v140, v125
	ds_write2st64_b32 v184, v137, v138 offset0:24 offset1:26
	v_add_f32_e32 v137, v140, v139
	v_add_f32_e32 v136, v140, v136
	v_add_f32_e32 v135, v140, v135
	v_add_f32_e32 v134, v140, v134
	v_add_f32_e32 v133, v140, v133
	v_add_f32_e32 v132, v140, v132
	v_add_f32_e32 v131, v140, v131
	v_add_f32_e32 v130, v140, v130
	v_add_f32_e32 v129, v140, v129
	v_add_f32_e32 v128, v140, v128
	ds_write2st64_b32 v184, v124, v125 offset0:48 offset1:50
	v_add_f32_e32 v124, v140, v126
	v_add_f32_e32 v125, v140, v127
	ds_write2st64_b32 v184, v137, v136 offset0:28 offset1:30
	ds_write2st64_b32 v184, v135, v134 offset0:32 offset1:34
	ds_write2st64_b32 v184, v133, v132 offset0:36 offset1:38
	ds_write2st64_b32 v184, v131, v130 offset0:40 offset1:42
	ds_write2st64_b32 v184, v129, v128 offset0:44 offset1:46
	ds_write2st64_b32 v184, v124, v125 offset0:52 offset1:54
	s_waitcnt lgkmcnt(0)
	s_barrier
	s_and_saveexec_b64 s[0:1], s[8:9]
	s_cbranch_execz .LBB0_582
	ds_read_b32 v124, v175 offset:6144
	v_lshl_add_u32 v125, s59, 9, v175
	s_waitcnt lgkmcnt(0)
	ds_write_b32 v125, v124 offset:4096
.LBB0_582:
	s_or_b64 exec, exec, s[0:1]
	s_cmp_gt_u32 s58, 2
	s_cbranch_scc1 .LBB0_589
	s_and_saveexec_b64 s[0:1], vcc
	s_and_b64 s[44:45], s[44:45], exec
	s_cselect_b32 s31, s54, 0xf0
	v_add_u32_e32 v124, s31, v250
	ds_write2_b32 v124, v0, v1 offset1:16
	ds_write2_b32 v124, v2, v3 offset0:32 offset1:48
	s_or_b64 exec, exec, s[0:1]
	s_cmp_eq_u32 s38, 0xfff40000
	s_cbranch_scc1 .LBB0_589
	s_ashr_i32 s31, s30, 31
	s_lshl_b64 s[0:1], s[30:31], 7
	s_add_u32 s0, s43, s0
	s_addc_u32 s1, s41, s1
	s_add_u32 s44, s0, 0x2100040
	s_addc_u32 s45, s1, 0
	s_and_saveexec_b64 s[0:1], vcc
	s_cbranch_execz .LBB0_588
	v_lshl_add_u64 v[0:1], s[44:45], 0, v[100:101]
	global_load_dwordx4 v[0:3], v[0:1], off

.LBB0_652:
	v_lshrrev_b32_e32 v250, 6, v154
	v_bfe_u32 v251, v154, 2, 2
	v_lshlrev_b32_e32 v250, 4, v250
	v_lshl_add_u32 v250, v251, 2, v250
	v_and_b32_e32 v251, 3, v154
	v_lshl_add_u32 v250, v251, 8, v250
	v_bfe_u32 v251, v154, 4, 2
	v_lshl_add_u32 v250, v251, 10, v250
	v_mov_b32_e32 v1, 0
	ds_read_b128 v[2:5], v1 offset:80
	ds_read2_b64 v[6:9], v1 offset0:12 offset1:27
	v_readlane_b32 s0, v240, 0
	s_cmpk_gt_i32 s0, 0xff
	s_waitcnt lgkmcnt(0)
	v_readfirstlane_b32 s45, v3
	v_readfirstlane_b32 s44, v2
	v_readfirstlane_b32 s47, v5
	v_readfirstlane_b32 s46, v4
	v_readfirstlane_b32 s49, v7
	v_readfirstlane_b32 s48, v6
	v_readfirstlane_b32 s51, v9
	v_readfirstlane_b32 s53, v8
	s_cbranch_scc1 .LBB0_698
	v_and_b32_e32 v11, 3, v154
	v_lshlrev_b32_e32 v21, 2, v154
	v_lshlrev_b32_e32 v174, 4, v11
	v_and_or_b32 v11, v21, 48, v11
	v_lshrrev_b32_e32 v13, 4, v154
	v_lshlrev_b32_e32 v177, 6, v11
	v_lshlrev_b32_e32 v11, 3, v154
	v_mul_u32_u24_e32 v15, 0x1800, v13
	v_lshlrev_b32_e32 v16, 4, v154
	s_movk_i32 s0, 0xf0
	s_movk_i32 s1, 0x100
	v_add_u32_e32 v178, 0xf0, v21
	v_and_b32_e32 v21, 0x78, v11
	v_mov_b32_e32 v22, 0xf0
	v_and_b32_e32 v5, 15, v154
	v_and_or_b32 v112, v16, s0, v15
	v_lshrrev_b32_e32 v15, 5, v154
	v_cmp_gt_u32_e64 s[2:3], s1, v154
	v_lshl_add_u32 v22, v21, 2, v22
	v_lshlrev_b32_e32 v21, 1, v21
	v_lshrrev_b32_e32 v24, 3, v154
	s_movk_i32 s1, 0x70
	v_bfe_u32 v7, v154, 4, 2
	v_mul_u32_u24_e32 v17, 0x1800, v15
	v_and_b32_e32 v18, 0x1f0, v16
	v_and_b32_e32 v16, 48, v154
	v_sub_u32_e32 v21, v22, v21
	v_and_or_b32 v24, v24, s1, v5
	s_mov_b32 s12, 0x1e800
	v_lshlrev_b32_e32 v31, 9, v13
	v_mul_u32_u24_e32 v13, 0x88, v13
	v_lshlrev_b32_e32 v170, 9, v7
	v_or_b32_e32 v114, v17, v18
	v_lshlrev_b32_e32 v175, 2, v7
	v_lshlrev_b32_e32 v17, 3, v7
	v_and_b32_e32 v19, 0x3c0, v154
	v_cmp_eq_u32_e64 s[8:9], 3, v7
	v_lshlrev_b32_e32 v7, 2, v5
	v_add_u32_e32 v179, 0xf0, v16
	v_mul_u32_u24_e32 v25, 0x90, v24
	s_addk_i32 s12, 0xf0
	v_lshl_add_u32 v181, v13, 1, v21
	v_add_u32_e32 v13, 0x200, v154
	v_or_b32_e32 v20, v19, v17
	v_add3_u32 v7, s0, v19, v7
	s_movk_i32 s0, 0x80
	v_add3_u32 v25, s12, v25, v17
	v_sub_u32_e32 v29, v179, v17
	v_lshrrev_b32_e32 v17, 4, v13
	v_cmp_gt_u32_e64 s[10:11], s0, v154
	s_mov_b32 s0, 0x16400
	v_lshlrev_b32_e32 v32, 9, v17
	v_mul_u32_u24_e32 v17, 0x88, v17
	s_addk_i32 s0, 0xf0
	v_lshl_add_u32 v182, v17, 1, v21
	v_add_u32_e32 v17, 0x600, v154
	v_add_u32_e32 v23, s0, v18
	v_and_b32_e32 v18, 2, v15
	v_bfe_u32 v26, v154, 2, 2
	v_lshrrev_b32_e32 v27, 1, v154
	v_and_b32_e32 v11, 24, v11
	v_lshrrev_b32_e32 v17, 5, v17
	v_and_or_b32 v26, v27, 24, v26
	v_add3_u32 v27, s0, v19, v11
	v_mul_u32_u24_e32 v21, 0x210, v17
	v_lshlrev_b32_e32 v17, 4, v18
	v_lshlrev_b32_e32 v35, 5, v18
	v_or_b32_e32 v18, 1, v18
	s_mov_b32 s0, 0x20c00
	v_and_b32_e32 v0, 63, v154
	v_or_b32_e32 v19, v17, v5
	v_or_b32_e32 v17, v17, v175
	v_lshlrev_b32_e32 v36, 4, v18
	s_addk_i32 s0, 0xf0
	v_cmp_gt_u32_e64 s[4:5], 16, v0
	v_cmp_lt_u32_e64 s[6:7], 31, v0
	v_or_b32_e32 v37, v36, v5
	v_or_b32_e32 v36, v36, v175
	v_cmp_gt_u32_e64 s[28:29], 32, v0
	v_or_b32_e32 v0, 1, v17
	s_add_u32 s82, s53, 0x6b20000
	v_lshrrev_b32_e32 v3, 6, v154
	s_movk_i32 s1, 0x110
	v_lshlrev_b32_e32 v40, 5, v18
	v_mov_b32_e32 v18, 0x2200
	v_cmp_lt_u32_e64 s[30:31], v0, v24
	v_or_b32_e32 v0, 1, v36
	s_addc_u32 s83, s51, 0
	v_mul_u32_u24_e32 v33, 0x110, v19
	v_or_b32_e32 v19, 2, v17
	v_mul_u32_u24_e32 v41, 0x210, v26
	v_mul_u32_u24_e32 v44, 0x110, v26
	v_mad_u32_u24 v26, v26, s1, v18
	v_mul_u32_u24_e32 v18, 0x1800, v5
	v_cmp_lt_u32_e64 s[38:39], v0, v24
	s_add_u32 s84, s53, 0x2100000
	v_lshlrev_b32_e32 v0, 7, v3
	v_writelane_b32 v240, s54, 13
	v_cmp_gt_u32_e64 s[16:17], v19, v24
	v_or_b32_e32 v118, v20, v18
	v_cmp_lt_u32_e64 s[34:35], v19, v24
	s_addc_u32 s85, s51, 0
	v_lshl_add_u64 v[18:19], s[48:49], 0, v[0:1]
	v_mbcnt_lo_u32_b32 v0, -1, 0
	v_writelane_b32 v240, s55, 14
	v_lshl_add_u32 v184, v5, 5, s0
	s_add_u32 s0, s53, 0xad20000
	v_mbcnt_hi_u32_b32 v0, -1, v0
	v_lshl_or_b32 v155, v3, 4, v5
	v_lshl_add_u32 v185, v3, 2, v184
	v_writelane_b32 v240, s0, 15
	s_addc_u32 s0, s51, 0
	v_and_b32_e32 v3, 64, v0
	v_lshl_or_b32 v116, v5, 11, v20
	v_mul_u32_u24_e32 v42, 0x90, v5
	v_mul_u32_u24_e32 v43, 0x110, v5
	v_writelane_b32 v240, s0, 17
	s_add_u32 s0, s53, 0x2920000
	v_or_b32_e32 v5, v3, v5
	v_writelane_b32 v240, s0, 19
	s_addc_u32 s0, s51, 0
	v_lshlrev_b32_e32 v186, 2, v5
	v_xor_b32_e32 v5, 16, v0
	v_add_u32_e32 v3, 64, v3
	v_writelane_b32 v240, s0, 21
	s_add_u32 s0, s53, 0x17320000
	v_cmp_lt_i32_e32 vcc, v5, v3
	v_writelane_b32 v240, s0, 23
	s_addc_u32 s0, s51, 0
	v_cndmask_b32_e32 v5, v0, v5, vcc
	v_lshrrev_b32_e32 v9, 2, v154
	v_writelane_b32 v240, s0, 25
	v_lshlrev_b32_e32 v190, 2, v5
	v_xor_b32_e32 v5, 32, v0
	s_add_u32 s0, s53, 0xad20800
	v_lshlrev_b32_e32 v176, 6, v9
	v_lshrrev_b32_e32 v13, 5, v13
	v_cmp_lt_i32_e32 vcc, v5, v3
	v_writelane_b32 v240, s0, 27
	v_or_b32_e32 v2, 0x400, v154
	v_or_b32_e32 v4, 0x800, v154
	v_or_b32_e32 v6, 0xc00, v154
	v_or_b32_e32 v8, 0x1000, v154
	v_or_b32_e32 v10, 0x1400, v154
	v_or_b32_e32 v12, 0x1800, v154
	v_or_b32_e32 v14, 0x1c00, v154
	v_lshl_or_b32 v110, v9, 7, v174
	v_add_u32_e32 v9, 0xf0, v176
	v_add_u32_e32 v28, s12, v16
	v_add_u32_e32 v11, 0xf0, v11
	v_lshlrev_b32_e32 v30, 9, v16
	v_mul_u32_u24_e32 v15, 0x210, v15
	v_mul_u32_u24_e32 v13, 0x210, v13
	v_cmp_gt_u32_e64 s[12:13], v17, v24
	v_cmp_lt_u32_e64 s[14:15], v17, v24
	v_or_b32_e32 v34, 3, v17
	v_mul_u32_u24_e32 v37, 0x110, v37
	v_or_b32_e32 v38, 2, v36
	v_or_b32_e32 v39, 3, v36
	v_mov_b32_e32 v17, v1
	v_cndmask_b32_e32 v0, v0, v5, vcc
	v_readlane_b32 s94, v240, 0
	v_or_b32_e32 v171, 0x800, v170
	v_or_b32_e32 v172, 0x1000, v170
	v_or_b32_e32 v173, 0x1800, v170
	v_mov_b32_e32 v111, v1
	v_mad_u32_u24 v180, v24, s1, v179
	v_mov_b32_e32 v113, v1
	v_mov_b32_e32 v115, v1
	v_cmp_gt_u32_e64 s[18:19], v34, v24
	v_cmp_gt_u32_e64 s[20:21], v36, v24
	v_cmp_lt_u32_e64 s[22:23], v36, v24
	v_cmp_gt_u32_e64 s[24:25], v38, v24
	v_cmp_gt_u32_e64 s[26:27], v39, v24
	v_mov_b32_e32 v117, v1
	s_movk_i32 s78, 0x2000
	v_or_b32_e32 v183, 0x2000, v155
	v_or_b32_e32 v120, 0x8000, v116
	v_mov_b32_e32 v121, v1
	v_or_b32_e32 v122, 0x8020, v116
	v_mov_b32_e32 v123, v1
	v_or_b32_e32 v124, 0x10000, v116
	v_mov_b32_e32 v125, v1
	v_or_b32_e32 v126, 0x10020, v116
	v_mov_b32_e32 v127, v1
	s_mov_b32 s81, 0x18000
	v_or_b32_e32 v128, 0x18000, v116
	v_mov_b32_e32 v129, v1
	v_or_b32_e32 v130, 0x18020, v116
	v_mov_b32_e32 v131, v1
	v_cmp_lt_u32_e64 s[36:37], v34, v24
	v_cmp_lt_u32_e64 s[40:41], v38, v24
	v_cmp_lt_u32_e64 s[42:43], v39, v24
	v_mov_b32_e32 v119, v1
	v_lshl_add_u64 v[132:133], v[18:19], 0, v[16:17]
	s_mov_b32 s49, 0
	v_or_b32_e32 v187, 64, v186
	v_or_b32_e32 v188, 0x80, v186
	v_or_b32_e32 v189, 0xc0, v186
	v_lshlrev_b32_e32 v191, 2, v0
	s_addc_u32 s89, s51, 0
	v_lshlrev_b32_e32 v192, 4, v2
	s_movk_i32 s79, 0x6000
	v_lshlrev_b32_e32 v193, 4, v4
	s_mov_b32 s91, 0xa000
	v_lshlrev_b32_e32 v194, 4, v6
	s_mov_b32 s92, 0xe000
	v_lshlrev_b32_e32 v195, 4, v8
	s_mov_b32 s66, 0x12000
	v_lshlrev_b32_e32 v196, 4, v10
	s_mov_b32 s93, 0x16000
	v_lshlrev_b32_e32 v197, 4, v12
	v_lshlrev_b32_e32 v198, 4, v14
	s_mov_b32 s95, 0x30000
	s_mov_b32 s96, 0x48000
	s_mov_b32 s97, 0xbfb8aa3b
	s_mov_b32 s0, 0x3d800000
	s_mov_b32 s50, 0x3db504f3
	s_mov_b32 s52, 0x3b800000
	s_mov_b32 s1, 0x800000
	v_add_u32_e32 v199, v9, v174
	v_add_u32_e32 v200, v7, v30
	v_add_u32_e32 v201, v22, v31
	v_add_u32_e32 v202, v22, v32
	v_add_u32_e32 v203, v23, v15
	v_add_u32_e32 v204, v23, v13
	v_add_u32_e32 v205, v23, v21
	v_add_u32_e32 v206, v179, v33
	v_add_u32_e32 v207, v25, v35
	v_add_u32_e32 v208, v179, v37
	v_add_u32_e32 v209, v25, v40
	v_add_u32_e32 v210, v27, v41
	v_add_u32_e32 v211, v28, v42
	v_add_u32_e32 v212, v29, v43
	v_add_u32_e32 v213, v11, v44
	v_add_u32_e32 v214, v11, v26
	s_mov_b32 s80, s94
	s_branch .LBB0_655

.LBB0_657:
	s_or_b64 exec, exec, s[58:59]
	s_and_saveexec_b64 s[56:57], s[2:3]
	s_cbranch_execz .LBB0_659
	s_waitcnt vmcnt(0)
	v_add_u32_e32 v251, 0xf0, v250
	ds_write2_b32 v251, v2, v3 offset1:16
	ds_write2_b32 v251, v4, v5 offset0:32 offset1:48

.LBB0_664:
	s_add_u32 s62, s61, s76
	s_addc_u32 s63, s91, s77
	v_lshl_add_u64 v[70:71], s[62:63], 0, v[112:113]
	s_add_u32 s62, s55, s76
	s_addc_u32 s63, s57, s77
	s_add_u32 s62, s62, s68
	v_add_co_u32_e32 v74, vcc, s95, v70
	s_addc_u32 s63, s63, 0
	s_nop 0
	v_addc_co_u32_e32 v75, vcc, 0, v71, vcc
	v_lshl_add_u64 v[86:87], s[62:63], 0, v[114:115]
	v_add_co_u32_e32 v78, vcc, s81, v86
	s_and_b32 s93, s92, 1
	s_add_i32 s69, s66, 0xf0
	v_addc_co_u32_e32 v79, vcc, 0, v87, vcc
	s_cmp_eq_u32 s93, 0
	v_add_co_u32_e32 v82, vcc, s95, v86
	s_cselect_b64 s[78:79], -1, 0
	s_nop 0
	v_addc_co_u32_e32 v83, vcc, 0, v87, vcc
	s_and_b64 s[62:63], s[78:79], exec
	global_load_dwordx4 v[94:97], v[70:71], off
	global_load_dwordx4 v[98:101], v[70:71], off offset:1024
	s_nop 0
	global_load_dwordx4 v[70:73], v[74:75], off
	global_load_dwordx4 v[90:93], v[74:75], off offset:1024
	s_cselect_b32 s62, 0xf0, s69
	global_load_dwordx4 v[74:77], v[86:87], off
	v_add_co_u32_e32 v86, vcc, s96, v86
	v_and_b32_e32 v137, 63, v154
	v_lshl_add_u32 v137, v137, 2, s62
	s_nop 0
	v_addc_co_u32_e32 v87, vcc, 0, v87, vcc
	global_load_dwordx4 v[78:81], v[78:79], off
	s_nop 0
	global_load_dwordx4 v[82:85], v[82:83], off
	s_nop 0
	global_load_dwordx4 v[86:89], v[86:87], off
	ds_read2st64_b32 v[134:135], v137 offset1:1
	ds_read2st64_b32 v[142:143], v137 offset0:2 offset1:3
	s_waitcnt lgkmcnt(1)
	v_mfma_f32_16x16x4_f32 v[138:141], v134, v104, 0
	ds_read2st64_b32 v[146:147], v137 offset0:8 offset1:9
	v_mfma_f32_16x16x4_f32 v[138:141], v135, v105, v[138:141]
	s_waitcnt lgkmcnt(1)
	v_mfma_f32_16x16x4_f32 v[138:141], v142, v106, v[138:141]
	v_mfma_f32_16x16x4_f32 v[138:141], v143, v107, v[138:141]
	ds_read2st64_b32 v[142:143], v137 offset0:4 offset1:5
	s_nop 8
	v_add_f32_e32 v134, v108, v138
	v_min_f32_e32 v109, 0, v134
	v_mul_f32_e64 v134, |v134|, s97
	v_exp_f32_e32 v134, v134
	v_add_f32_e32 v135, v108, v139
	v_add_f32_e32 v136, v108, v140
	v_add_f32_e32 v138, v108, v141
	v_add_f32_e32 v134, 1.0, v134
	v_log_f32_e32 v134, v134
	s_nop 0
	v_fmac_f32_e32 v109, 0xbf317218, v134
	v_min_f32_e32 v134, 0, v135
	v_mul_f32_e64 v135, |v135|, s97
	v_exp_f32_e32 v135, v135
	v_fma_f32 v109, v109, s0, 0
	v_add_f32_e32 v135, 1.0, v135
	v_log_f32_e32 v135, v135
	s_nop 0
	v_fmac_f32_e32 v134, 0xbf317218, v135
	v_min_f32_e32 v135, 0, v136
	v_mul_f32_e64 v136, |v136|, s97
	v_exp_f32_e32 v136, v136
	v_fmamk_f32 v134, v134, 0x3d800000, v109
	v_add_f32_e32 v136, 1.0, v136
	v_log_f32_e32 v136, v136
	s_nop 0
	v_fmac_f32_e32 v135, 0xbf317218, v136
	v_min_f32_e32 v136, 0, v138
	v_mul_f32_e64 v138, |v138|, s97
	v_exp_f32_e32 v138, v138
	v_fmamk_f32 v135, v135, 0x3d800000, v134
	v_add_f32_e32 v138, 1.0, v138
	v_log_f32_e32 v138, v138
	s_nop 0
	v_fmac_f32_e32 v136, 0xbf317218, v138
	s_waitcnt lgkmcnt(0)
	v_mfma_f32_16x16x4_f32 v[138:141], v142, v104, 0
	v_fmamk_f32 v136, v136, 0x3d800000, v135
	v_mfma_f32_16x16x4_f32 v[138:141], v143, v105, v[138:141]
	ds_read2st64_b32 v[142:143], v137 offset0:6 offset1:7
	s_waitcnt lgkmcnt(0)
	v_mfma_f32_16x16x4_f32 v[138:141], v142, v106, v[138:141]
	v_mfma_f32_16x16x4_f32 v[138:141], v143, v107, v[138:141]
	s_nop 9
	v_add_f32_e32 v142, v108, v138
	v_min_f32_e32 v138, 0, v142
	v_mul_f32_e64 v142, |v142|, s97
	v_exp_f32_e32 v142, v142
	s_nop 0
	v_add_f32_e32 v142, 1.0, v142
	v_log_f32_e32 v142, v142
	s_nop 0
	v_fmac_f32_e32 v138, 0xbf317218, v142
	v_add_f32_e32 v142, v108, v139
	v_min_f32_e32 v139, 0, v142
	v_mul_f32_e64 v142, |v142|, s97
	v_exp_f32_e32 v142, v142
	s_nop 0
	v_add_f32_e32 v142, 1.0, v142
	v_log_f32_e32 v142, v142
	s_nop 0
	v_fmac_f32_e32 v139, 0xbf317218, v142
	v_add_f32_e32 v142, v108, v140
	v_min_f32_e32 v140, 0, v142
	v_mul_f32_e64 v142, |v142|, s97
	v_exp_f32_e32 v142, v142
	s_nop 0
	v_add_f32_e32 v142, 1.0, v142
	v_log_f32_e32 v142, v142
	s_nop 0
	v_fmac_f32_e32 v140, 0xbf317218, v142
	v_add_f32_e32 v142, v108, v141
	v_min_f32_e32 v141, 0, v142
	v_mul_f32_e64 v142, |v142|, s97
	v_exp_f32_e32 v142, v142
	s_nop 0
	v_add_f32_e32 v142, 1.0, v142
	v_log_f32_e32 v142, v142
	s_nop 0
	v_fmac_f32_e32 v141, 0xbf317218, v142
	v_mfma_f32_16x16x4_f32 v[142:145], v146, v104, 0
	v_mfma_f32_16x16x4_f32 v[142:145], v147, v105, v[142:145]
	ds_read2st64_b32 v[146:147], v137 offset0:10 offset1:11
	s_waitcnt lgkmcnt(0)
	v_mfma_f32_16x16x4_f32 v[142:145], v146, v106, v[142:145]
	v_mfma_f32_16x16x4_f32 v[142:145], v147, v107, v[142:145]
	ds_read2st64_b32 v[146:147], v137 offset0:12 offset1:13
	s_nop 8
	v_add_f32_e32 v142, v108, v142
	v_min_f32_e32 v148, 0, v142
	v_mul_f32_e64 v142, |v142|, s97
	v_exp_f32_e32 v142, v142
	s_nop 0
	v_add_f32_e32 v142, 1.0, v142
	v_log_f32_e32 v142, v142
	s_nop 0
	v_fmac_f32_e32 v148, 0xbf317218, v142
	v_add_f32_e32 v142, v108, v143
	v_min_f32_e32 v149, 0, v142
	v_mul_f32_e64 v142, |v142|, s97
	v_exp_f32_e32 v142, v142
	s_nop 0
	v_add_f32_e32 v142, 1.0, v142
	v_log_f32_e32 v142, v142
	s_nop 0
	v_fmac_f32_e32 v149, 0xbf317218, v142
	v_add_f32_e32 v142, v108, v144
	v_min_f32_e32 v150, 0, v142
	v_mul_f32_e64 v142, |v142|, s97
	v_exp_f32_e32 v142, v142
	s_nop 0
	v_add_f32_e32 v142, 1.0, v142
	v_log_f32_e32 v142, v142
	s_nop 0
	v_fmac_f32_e32 v150, 0xbf317218, v142
	v_add_f32_e32 v142, v108, v145
	v_min_f32_e32 v151, 0, v142
	v_mul_f32_e64 v142, |v142|, s97
	v_exp_f32_e32 v142, v142
	s_nop 0
	v_add_f32_e32 v142, 1.0, v142
	v_log_f32_e32 v142, v142
	s_nop 0
	v_fmac_f32_e32 v151, 0xbf317218, v142
	s_waitcnt lgkmcnt(0)
	v_mfma_f32_16x16x4_f32 v[142:145], v146, v104, 0
	v_mfma_f32_16x16x4_f32 v[142:145], v147, v105, v[142:145]
	ds_read2st64_b32 v[146:147], v137 offset0:14 offset1:15
	s_waitcnt lgkmcnt(0)
	v_mfma_f32_16x16x4_f32 v[142:145], v146, v106, v[142:145]
	v_mfma_f32_16x16x4_f32 v[142:145], v147, v107, v[142:145]
	s_nop 9
	v_add_f32_e32 v137, v108, v142
	v_min_f32_e32 v142, 0, v137
	v_mul_f32_e64 v137, |v137|, s97
	v_exp_f32_e32 v137, v137
	s_nop 0
	v_add_f32_e32 v137, 1.0, v137
	v_log_f32_e32 v137, v137
	s_nop 0
	v_fmac_f32_e32 v142, 0xbf317218, v137
	v_add_f32_e32 v137, v108, v143
	v_min_f32_e32 v143, 0, v137
	v_mul_f32_e64 v137, |v137|, s97
	v_exp_f32_e32 v137, v137
	s_nop 0
	v_add_f32_e32 v137, 1.0, v137
	v_log_f32_e32 v137, v137
	s_nop 0
	v_fmac_f32_e32 v143, 0xbf317218, v137
	v_add_f32_e32 v137, v108, v144
	v_min_f32_e32 v144, 0, v137
	v_mul_f32_e64 v137, |v137|, s97
	v_exp_f32_e32 v137, v137
	s_nop 0
	v_add_f32_e32 v137, 1.0, v137
	v_log_f32_e32 v137, v137
	s_nop 0
	v_fmac_f32_e32 v144, 0xbf317218, v137
	v_add_f32_e32 v137, v108, v145
	v_min_f32_e32 v145, 0, v137
	v_mul_f32_e64 v137, |v137|, s97
	v_exp_f32_e32 v137, v137
	s_nop 0
	v_add_f32_e32 v137, 1.0, v137
	v_log_f32_e32 v137, v137
	s_nop 0
	v_fmac_f32_e32 v145, 0xbf317218, v137
	v_fmamk_f32 v137, v138, 0x3d800000, v136
	v_fmamk_f32 v138, v139, 0x3d800000, v137
	v_fmamk_f32 v139, v140, 0x3d800000, v138
	v_fmamk_f32 v140, v141, 0x3d800000, v139
	v_fmamk_f32 v141, v148, 0x3d800000, v140
	v_fmamk_f32 v146, v149, 0x3d800000, v141
	v_fmamk_f32 v147, v150, 0x3d800000, v146
	v_fmamk_f32 v148, v151, 0x3d800000, v147
	v_fmamk_f32 v142, v142, 0x3d800000, v148
	v_fmamk_f32 v143, v143, 0x3d800000, v142
	v_fmamk_f32 v144, v144, 0x3d800000, v143
	v_fmamk_f32 v145, v145, 0x3d800000, v144
	ds_bpermute_b32 v149, v186, v145
	ds_bpermute_b32 v150, v187, v145
	ds_bpermute_b32 v151, v188, v145
	s_waitcnt lgkmcnt(2)
	v_cndmask_b32_e64 v149, v149, 0, s[4:5]
	s_waitcnt lgkmcnt(1)
	v_cndmask_b32_e64 v150, 0, v150, s[6:7]
	v_add_f32_e32 v149, v149, v150
	s_waitcnt lgkmcnt(0)
	v_cndmask_b32_e64 v150, 0, v151, s[8:9]
	v_add_f32_e32 v149, v149, v150
	v_add_f32_e32 v109, v109, v149
	v_add_f32_e32 v134, v134, v149
	ds_write2st64_b32 v200, v109, v134 offset0:24 offset1:26
	v_add_f32_e32 v109, v135, v149
	v_add_f32_e32 v134, v136, v149
	ds_write2st64_b32 v200, v109, v134 offset0:28 offset1:30
	v_add_f32_e32 v109, v137, v149
	v_add_f32_e32 v134, v138, v149
	ds_write2st64_b32 v200, v109, v134 offset0:32 offset1:34
	v_add_f32_e32 v109, v139, v149
	v_add_f32_e32 v134, v140, v149
	ds_write2st64_b32 v200, v109, v134 offset0:36 offset1:38
	v_add_f32_e32 v109, v141, v149
	v_add_f32_e32 v134, v146, v149
	ds_write2st64_b32 v200, v109, v134 offset0:40 offset1:42
	v_add_f32_e32 v109, v149, v147
	v_add_f32_e32 v134, v149, v148
	ds_write2st64_b32 v200, v109, v134 offset0:44 offset1:46
	v_add_f32_e32 v109, v149, v142
	v_add_f32_e32 v134, v149, v143
	ds_write2st64_b32 v200, v109, v134 offset0:48 offset1:50
	v_add_f32_e32 v109, v149, v144
	v_add_f32_e32 v134, v149, v145
	ds_write2st64_b32 v200, v109, v134 offset0:52 offset1:54
	s_waitcnt lgkmcnt(0)
	s_barrier
	s_and_saveexec_b64 s[62:63], s[10:11]
	s_cbranch_execz .LBB0_666
	ds_read_b32 v109, v178 offset:38400
	v_lshl_add_u32 v134, s93, 9, v178
	s_waitcnt lgkmcnt(0)
	ds_write_b32 v134, v109 offset:4096
.LBB0_666:
	s_or_b64 exec, exec, s[62:63]
	s_cmp_gt_u32 s92, 6
	s_cbranch_scc1 .LBB0_663
	s_and_saveexec_b64 s[62:63], s[2:3]
	s_and_b64 s[70:71], s[78:79], exec
	s_cselect_b32 s65, s69, 0xf0
	v_add_u32_e32 v109, s65, v250
	ds_write2_b32 v109, v2, v3 offset1:16
	ds_write2_b32 v109, v4, v5 offset0:32 offset1:48
	s_or_b64 exec, exec, s[62:63]
	s_cmp_eq_u32 s76, 0x240000
	s_cbranch_scc1 .LBB0_663
	s_ashr_i32 s65, s64, 31
	s_lshl_b64 s[62:63], s[64:65], 7
	s_add_u32 s70, s84, s62
	s_addc_u32 s71, s85, s63
	s_and_saveexec_b64 s[62:63], s[2:3]
	s_cbranch_execz .LBB0_662
	v_lshl_add_u64 v[2:3], s[70:71], 0, v[110:111]
	global_load_dwordx4 v[2:5], v[2:3], off
	s_branch .LBB0_662

.LBB0_674:
	s_or_b64 exec, exec, s[62:63]
	s_and_saveexec_b64 s[60:61], s[2:3]
	s_cbranch_execz .LBB0_676
	s_waitcnt vmcnt(0)
	v_add_u32_e32 v251, 0xf0, v250
	ds_write2_b32 v251, v2, v3 offset1:16
	ds_write2_b32 v251, v4, v5 offset0:32 offset1:48

.LBB0_680:
	s_add_u32 s62, s71, s60
	s_addc_u32 s63, s74, s61
	s_add_u32 s72, s48, s60
	s_addc_u32 s73, s70, s61
	s_add_u32 s55, s72, s68
	v_lshl_add_u64 v[70:71], s[62:63], 0, v[112:113]
	s_addc_u32 s63, s73, 0
	s_add_u32 s62, s55, 0xafc0800
	v_add_co_u32_e32 v74, vcc, s95, v70
	s_addc_u32 s63, s63, 0
	s_nop 0
	v_addc_co_u32_e32 v75, vcc, 0, v71, vcc
	v_lshl_add_u64 v[86:87], s[62:63], 0, v[114:115]
	v_add_co_u32_e32 v78, vcc, s81, v86
	s_and_b32 s67, s75, 1
	s_nop 0
	v_addc_co_u32_e32 v79, vcc, 0, v87, vcc
	s_cmp_eq_u32 s67, 0
	v_add_co_u32_e32 v82, vcc, s95, v86
	s_cselect_b64 s[64:65], -1, 0
	s_nop 0
	v_addc_co_u32_e32 v83, vcc, 0, v87, vcc
	s_and_b64 s[62:63], s[64:65], exec
	global_load_dwordx4 v[94:97], v[70:71], off
	global_load_dwordx4 v[98:101], v[70:71], off offset:1024
	s_nop 0
	global_load_dwordx4 v[70:73], v[74:75], off
	global_load_dwordx4 v[90:93], v[74:75], off offset:1024
	s_cselect_b32 s55, 0xf0, s69
	global_load_dwordx4 v[74:77], v[86:87], off
	v_add_co_u32_e32 v86, vcc, s96, v86
	v_and_b32_e32 v105, 63, v154
	v_lshl_add_u32 v105, v105, 2, s55
	s_nop 0
	v_addc_co_u32_e32 v87, vcc, 0, v87, vcc
	global_load_dwordx4 v[78:81], v[78:79], off
	s_nop 0
	global_load_dwordx4 v[82:85], v[82:83], off
	s_nop 0
	global_load_dwordx4 v[86:89], v[86:87], off
	ds_read2st64_b32 v[102:103], v105 offset1:1
	ds_read2st64_b32 v[136:137], v105 offset0:2 offset1:3
	s_waitcnt vmcnt(12) lgkmcnt(1)
	v_mfma_f32_16x16x4_f32 v[106:109], v102, v219, 0
	ds_read2st64_b32 v[140:141], v105 offset0:8 offset1:9
	s_waitcnt vmcnt(11)
	v_mfma_f32_16x16x4_f32 v[106:109], v103, v220, v[106:109]
	s_waitcnt vmcnt(10) lgkmcnt(1)
	v_mfma_f32_16x16x4_f32 v[106:109], v136, v221, v[106:109]
	s_waitcnt vmcnt(9)
	v_mfma_f32_16x16x4_f32 v[106:109], v137, v222, v[106:109]
	ds_read2st64_b32 v[136:137], v105 offset0:4 offset1:5
	s_waitcnt vmcnt(8)
	s_nop 7
	v_add_f32_e32 v102, v223, v106
	v_min_f32_e32 v0, 0, v102
	v_mul_f32_e64 v102, |v102|, s97
	v_exp_f32_e32 v102, v102
	v_add_f32_e32 v103, v223, v107
	v_add_f32_e32 v104, v223, v108
	v_add_f32_e32 v106, v223, v109
	v_add_f32_e32 v102, 1.0, v102
	v_log_f32_e32 v102, v102
	s_nop 0
	v_fmac_f32_e32 v0, 0xbf317218, v102
	v_min_f32_e32 v102, 0, v103
	v_mul_f32_e64 v103, |v103|, s97
	v_exp_f32_e32 v103, v103
	s_nop 0
	v_add_f32_e32 v103, 1.0, v103
	v_log_f32_e32 v103, v103
	s_nop 0
	v_fmac_f32_e32 v102, 0xbf317218, v103
	v_min_f32_e32 v103, 0, v104
	v_mul_f32_e64 v104, |v104|, s97
	v_exp_f32_e32 v104, v104
	s_nop 0
	v_add_f32_e32 v104, 1.0, v104
	v_log_f32_e32 v104, v104
	s_nop 0
	v_fmac_f32_e32 v103, 0xbf317218, v104
	v_min_f32_e32 v104, 0, v106
	v_mul_f32_e64 v106, |v106|, s97
	v_exp_f32_e32 v106, v106
	s_nop 0
	v_add_f32_e32 v106, 1.0, v106
	v_log_f32_e32 v106, v106
	s_nop 0
	v_fmac_f32_e32 v104, 0xbf317218, v106
	s_waitcnt lgkmcnt(0)
	v_mfma_f32_16x16x4_f32 v[106:109], v136, v219, 0
	v_mfma_f32_16x16x4_f32 v[106:109], v137, v220, v[106:109]
	ds_read2st64_b32 v[136:137], v105 offset0:6 offset1:7
	s_waitcnt lgkmcnt(0)
	v_mfma_f32_16x16x4_f32 v[106:109], v136, v221, v[106:109]
	v_mfma_f32_16x16x4_f32 v[106:109], v137, v222, v[106:109]
	s_nop 9
	v_add_f32_e32 v136, v223, v106
	v_min_f32_e32 v106, 0, v136
	v_mul_f32_e64 v136, |v136|, s97
	v_exp_f32_e32 v136, v136
	s_nop 0
	v_add_f32_e32 v136, 1.0, v136
	v_log_f32_e32 v136, v136
	s_nop 0
	v_fmac_f32_e32 v106, 0xbf317218, v136
	v_add_f32_e32 v136, v223, v107
	v_min_f32_e32 v107, 0, v136
	v_mul_f32_e64 v136, |v136|, s97
	v_exp_f32_e32 v136, v136
	s_nop 0
	v_add_f32_e32 v136, 1.0, v136
	v_log_f32_e32 v136, v136
	s_nop 0
	v_fmac_f32_e32 v107, 0xbf317218, v136
	v_add_f32_e32 v136, v223, v108
	v_min_f32_e32 v108, 0, v136
	v_mul_f32_e64 v136, |v136|, s97
	v_exp_f32_e32 v136, v136
	s_nop 0
	v_add_f32_e32 v136, 1.0, v136
	v_log_f32_e32 v136, v136
	s_nop 0
	v_fmac_f32_e32 v108, 0xbf317218, v136
	v_add_f32_e32 v136, v223, v109
	v_min_f32_e32 v109, 0, v136
	v_mul_f32_e64 v136, |v136|, s97
	v_exp_f32_e32 v136, v136
	s_nop 0
	v_add_f32_e32 v136, 1.0, v136
	v_log_f32_e32 v136, v136
	s_nop 0
	v_fmac_f32_e32 v109, 0xbf317218, v136
	v_mfma_f32_16x16x4_f32 v[136:139], v140, v219, 0
	v_mfma_f32_16x16x4_f32 v[136:139], v141, v220, v[136:139]
	ds_read2st64_b32 v[140:141], v105 offset0:10 offset1:11
	s_waitcnt lgkmcnt(0)
	v_mfma_f32_16x16x4_f32 v[136:139], v140, v221, v[136:139]
	v_mfma_f32_16x16x4_f32 v[136:139], v141, v222, v[136:139]
	ds_read2st64_b32 v[140:141], v105 offset0:12 offset1:13
	s_nop 8
	v_add_f32_e32 v136, v223, v136
	v_min_f32_e32 v142, 0, v136
	v_mul_f32_e64 v136, |v136|, s97
	v_exp_f32_e32 v136, v136
	s_nop 0
	v_add_f32_e32 v136, 1.0, v136
	v_log_f32_e32 v136, v136
	s_nop 0
	v_fmac_f32_e32 v142, 0xbf317218, v136
	v_add_f32_e32 v136, v223, v137
	v_min_f32_e32 v143, 0, v136
	v_mul_f32_e64 v136, |v136|, s97
	v_exp_f32_e32 v136, v136
	s_nop 0
	v_add_f32_e32 v136, 1.0, v136
	v_log_f32_e32 v136, v136
	s_nop 0
	v_fmac_f32_e32 v143, 0xbf317218, v136
	v_add_f32_e32 v136, v223, v138
	v_min_f32_e32 v144, 0, v136
	v_mul_f32_e64 v136, |v136|, s97
	v_exp_f32_e32 v136, v136
	s_nop 0
	v_add_f32_e32 v136, 1.0, v136
	v_log_f32_e32 v136, v136
	s_nop 0
	v_fmac_f32_e32 v144, 0xbf317218, v136
	v_add_f32_e32 v136, v223, v139
	v_min_f32_e32 v145, 0, v136
	v_mul_f32_e64 v136, |v136|, s97
	v_exp_f32_e32 v136, v136
	s_nop 0
	v_add_f32_e32 v136, 1.0, v136
	v_log_f32_e32 v136, v136
	s_nop 0
	v_fmac_f32_e32 v145, 0xbf317218, v136
	s_waitcnt lgkmcnt(0)
	v_mfma_f32_16x16x4_f32 v[136:139], v140, v219, 0
	v_mfma_f32_16x16x4_f32 v[136:139], v141, v220, v[136:139]
	ds_read2st64_b32 v[140:141], v105 offset0:14 offset1:15
	s_waitcnt lgkmcnt(0)
	v_mfma_f32_16x16x4_f32 v[136:139], v140, v221, v[136:139]
	v_mfma_f32_16x16x4_f32 v[136:139], v141, v222, v[136:139]
	s_nop 9
	v_add_f32_e32 v105, v223, v136
	v_min_f32_e32 v136, 0, v105
	v_mul_f32_e64 v105, |v105|, s97
	v_exp_f32_e32 v105, v105
	s_nop 0
	v_add_f32_e32 v105, 1.0, v105
	v_log_f32_e32 v105, v105
	s_nop 0
	v_fmac_f32_e32 v136, 0xbf317218, v105
	v_add_f32_e32 v105, v223, v137
	v_min_f32_e32 v137, 0, v105
	v_mul_f32_e64 v105, |v105|, s97
	v_exp_f32_e32 v105, v105
	s_nop 0
	v_add_f32_e32 v105, 1.0, v105
	v_log_f32_e32 v105, v105
	s_nop 0
	v_fmac_f32_e32 v137, 0xbf317218, v105
	v_add_f32_e32 v105, v223, v138
	v_min_f32_e32 v138, 0, v105
	v_mul_f32_e64 v105, |v105|, s97
	v_exp_f32_e32 v105, v105
	s_nop 0
	v_add_f32_e32 v105, 1.0, v105
	v_log_f32_e32 v105, v105
	s_nop 0
	v_fmac_f32_e32 v138, 0xbf317218, v105
	v_add_f32_e32 v105, v223, v139
	v_min_f32_e32 v139, 0, v105
	v_mul_f32_e64 v105, |v105|, s97
	v_exp_f32_e32 v105, v105
	s_nop 0
	v_add_f32_e32 v105, 1.0, v105
	v_log_f32_e32 v105, v105
	s_nop 0
	v_fmac_f32_e32 v139, 0xbf317218, v105
	v_fma_f32 v105, v139, s0, 0
	v_fmamk_f32 v138, v138, 0x3d800000, v105
	v_fmamk_f32 v137, v137, 0x3d800000, v138
	v_fmamk_f32 v136, v136, 0x3d800000, v137
	v_fmamk_f32 v139, v145, 0x3d800000, v136
	v_fmamk_f32 v140, v144, 0x3d800000, v139
	v_fmamk_f32 v141, v143, 0x3d800000, v140
	v_fmamk_f32 v142, v142, 0x3d800000, v141
	v_fmamk_f32 v109, v109, 0x3d800000, v142
	v_fmamk_f32 v108, v108, 0x3d800000, v109
	v_fmamk_f32 v107, v107, 0x3d800000, v108
	v_fmamk_f32 v106, v106, 0x3d800000, v107
	v_fmamk_f32 v104, v104, 0x3d800000, v106
	v_fmamk_f32 v103, v103, 0x3d800000, v104
	v_fmamk_f32 v102, v102, 0x3d800000, v103
	v_fmamk_f32 v0, v0, 0x3d800000, v102
	ds_bpermute_b32 v144, v188, v0
	ds_bpermute_b32 v145, v189, v0
	ds_bpermute_b32 v143, v187, v0
	s_waitcnt lgkmcnt(2)
	v_cndmask_b32_e64 v144, 0, v144, s[28:29]
	s_waitcnt lgkmcnt(1)
	v_cndmask_b32_e64 v145, v145, 0, s[8:9]
	v_add_f32_e32 v144, v144, v145
	s_waitcnt lgkmcnt(0)
	v_cndmask_b32_e64 v143, 0, v143, s[4:5]
	v_add_f32_e32 v143, v143, v144
	v_add_f32_e32 v0, v143, v0
	v_add_f32_e32 v102, v143, v102
	ds_write2st64_b32 v200, v0, v102 offset0:24 offset1:26
	v_add_f32_e32 v0, v143, v103
	v_add_f32_e32 v102, v143, v104
	ds_write2st64_b32 v200, v0, v102 offset0:28 offset1:30
	v_add_f32_e32 v0, v143, v106
	v_add_f32_e32 v102, v143, v107
	ds_write2st64_b32 v200, v0, v102 offset0:32 offset1:34
	v_add_f32_e32 v0, v143, v108
	v_add_f32_e32 v102, v143, v109
	ds_write2st64_b32 v200, v0, v102 offset0:36 offset1:38
	v_add_f32_e32 v0, v143, v142
	v_add_f32_e32 v102, v143, v141
	ds_write2st64_b32 v200, v0, v102 offset0:40 offset1:42
	v_add_f32_e32 v0, v143, v140
	v_add_f32_e32 v102, v143, v139
	ds_write2st64_b32 v200, v0, v102 offset0:44 offset1:46
	v_add_f32_e32 v0, v143, v136
	v_add_f32_e32 v102, v143, v137
	ds_write2st64_b32 v200, v0, v102 offset0:48 offset1:50
	v_add_f32_e32 v0, v143, v138
	v_add_f32_e32 v102, v143, v105
	ds_write2st64_b32 v200, v0, v102 offset0:52 offset1:54
	s_waitcnt lgkmcnt(0)
	s_barrier
	s_and_saveexec_b64 s[62:63], s[10:11]
	s_cbranch_execz .LBB0_682
	ds_read_b32 v0, v178 offset:6144
	v_lshl_add_u32 v102, s67, 9, v178
	s_waitcnt lgkmcnt(0)
	ds_write_b32 v102, v0 offset:4096
.LBB0_682:
	s_or_b64 exec, exec, s[62:63]
	s_cmp_gt_u32 s75, 6
	s_cbranch_scc1 .LBB0_689
	s_and_saveexec_b64 s[62:63], s[2:3]
	s_and_b64 s[64:65], s[64:65], exec
	s_cselect_b32 s55, s69, 0xf0
	v_add_u32_e32 v0, s55, v250
	ds_write2_b32 v0, v2, v3 offset1:16
	ds_write2_b32 v0, v4, v5 offset0:32 offset1:48
	s_or_b64 exec, exec, s[62:63]
	s_cmp_eq_u32 s60, 0xffdc0000
	s_cbranch_scc1 .LBB0_689
	s_ashr_i32 s55, s54, 31
	s_lshl_b64 s[62:63], s[54:55], 7
	s_add_u32 s55, s53, s62
	s_addc_u32 s62, s51, s63
	s_add_u32 s64, s55, 0x2100040
	s_addc_u32 s65, s62, 0
	s_and_saveexec_b64 s[62:63], s[2:3]
	s_cbranch_execz .LBB0_688
	v_lshl_add_u64 v[2:3], s[64:65], 0, v[110:111]
	global_load_dwordx4 v[2:5], v[2:3], off

.LBB0_2071:
	v_lshrrev_b32_e32 v250, 6, v154
	v_bfe_u32 v251, v154, 2, 2
	v_lshlrev_b32_e32 v250, 4, v250
	v_lshl_add_u32 v250, v251, 2, v250
	v_and_b32_e32 v251, 3, v154
	v_lshl_add_u32 v250, v251, 8, v250
	v_bfe_u32 v251, v154, 4, 2
	v_lshl_add_u32 v250, v251, 10, v250
	v_mov_b32_e32 v0, 0
	ds_read_b128 v[2:5], v0 offset:80
	ds_read_b64 v[6:7], v0 offset:216
	v_readlane_b32 s2, v240, 0
	s_cmpk_gt_i32 s2, 0x1ff
	s_waitcnt lgkmcnt(0)
	v_readfirstlane_b32 s17, v3
	v_readfirstlane_b32 s16, v2
	v_readfirstlane_b32 s19, v5
	v_readfirstlane_b32 s18, v4
	v_readfirstlane_b32 s21, v7
	v_readfirstlane_b32 s20, v6
	s_cbranch_scc1 .LBB0_2114
	v_lshrrev_b32_e32 v4, 2, v154
	v_and_b32_e32 v3, 15, v154
	v_and_b32_e32 v5, 0xf0, v4
	s_movk_i32 s4, 0xf0
	v_or_b32_e32 v105, v5, v3
	v_lshlrev_b32_e32 v5, 2, v5
	v_lshlrev_b32_e32 v11, 2, v3
	v_add3_u32 v11, s4, v5, v11
	v_lshlrev_b32_e32 v5, 3, v154
	s_mov_b32 s6, 0x16400
	v_bfe_u32 v14, v154, 2, 2
	v_lshrrev_b32_e32 v15, 1, v154
	v_and_b32_e32 v12, 0x78, v5
	s_addk_i32 s6, 0xf0
	v_and_or_b32 v14, v15, 24, v14
	v_and_b32_e32 v15, 0x3c0, v154
	v_and_b32_e32 v5, 24, v5
	v_add3_u32 v15, s6, v15, v5
	v_add_u32_e32 v16, 0xf0, v5
	v_add_u32_e32 v5, 0x200, v154
	v_lshrrev_b32_e32 v17, 4, v5
	v_lshrrev_b32_e32 v5, 5, v5
	v_mul_u32_u24_e32 v19, 0x210, v5
	v_add_u32_e32 v5, 0x600, v154
	v_lshrrev_b32_e32 v5, 5, v5
	v_and_b32_e32 v6, 3, v154
	s_movk_i32 s14, 0x110
	v_mul_u32_u24_e32 v20, 0x210, v5
	v_mov_b32_e32 v5, 0x2200
	v_bfe_u32 v104, v154, 4, 2
	v_lshlrev_b32_e32 v107, 4, v6
	v_mul_u32_u24_e32 v21, 0x210, v14
	v_mul_u32_u24_e32 v22, 0x110, v14
	v_mad_u32_u24 v14, v14, s14, v5
	v_mov_b32_e32 v5, 0x4000
	v_lshl_or_b32 v94, v4, 7, v107
	v_lshlrev_b32_e32 v108, 6, v4
	v_lshlrev_b32_e32 v4, 2, v154
	v_lshl_or_b32 v112, v104, 9, v5
	v_mov_b32_e32 v5, v0
	v_and_or_b32 v6, v4, 48, v6
	v_add_u32_e32 v110, 0xf0, v4
	v_lshl_add_u64 v[4:5], s[20:21], 0, v[4:5]
	s_mov_b64 s[14:15], 0xab20000
	v_lshl_add_u64 v[100:101], v[4:5], 0, s[14:15]
	v_mbcnt_lo_u32_b32 v4, -1, 0
	v_lshrrev_b32_e32 v7, 4, v154
	v_mbcnt_hi_u32_b32 v4, -1, v4
	v_mul_u32_u24_e32 v8, 0x1800, v7
	v_lshlrev_b32_e32 v2, 4, v154
	v_and_or_b32 v3, v4, 64, v3
	v_and_or_b32 v96, v2, s4, v8
	v_lshrrev_b32_e32 v8, 5, v154
	v_mov_b32_e32 v13, 0xf0
	s_add_u32 s35, s20, 0x2100000
	v_lshlrev_b32_e32 v113, 2, v3
	v_mov_b32_e32 v3, v0
	v_and_b32_e32 v1, 63, v154
	v_mul_u32_u24_e32 v9, 0x1800, v8
	v_and_b32_e32 v10, 0x1f0, v2
	v_lshlrev_b32_e32 v109, 6, v6
	v_and_b32_e32 v6, 48, v154
	v_lshl_add_u32 v13, v12, 2, v13
	v_lshlrev_b32_e32 v12, 1, v12
	s_addc_u32 s36, s21, 0
	v_lshl_add_u64 v[2:3], s[20:21], 0, v[2:3]
	s_mov_b64 s[14:15], 0x6b20000
	v_or_b32_e32 v98, v9, v10
	s_movk_i32 s2, 0x100
	v_add_u32_e32 v9, 0xf0, v108
	s_movk_i32 s4, 0x80
	v_sub_u32_e32 v12, v13, v12
	v_add_u32_e32 v10, s6, v10
	v_add_u32_e32 v111, 0xf0, v6
	v_cmp_gt_u32_e64 s[8:9], 32, v1
	v_cmp_gt_u32_e64 s[10:11], 16, v1
	v_cmp_lt_u32_e64 s[12:13], 31, v1
	v_lshlrev_b32_e32 v1, 9, v6
	v_lshlrev_b32_e32 v6, 9, v7
	v_mul_u32_u24_e32 v7, 0x110, v7
	v_lshlrev_b32_e32 v18, 9, v17
	v_mul_u32_u24_e32 v17, 0x110, v17
	v_mul_u32_u24_e32 v8, 0x210, v8
	s_add_u32 s37, s20, 0xad20000
	v_lshl_add_u64 v[102:103], v[2:3], 0, s[14:15]
	s_mov_b32 s45, 0x12000
	v_readlane_b32 s14, v240, 0
	v_or_b32_e32 v106, 0x400, v105
	v_cmp_gt_u32_e64 s[2:3], s2, v154
	v_mov_b32_e32 v95, v0
	v_mov_b32_e32 v97, v0
	v_mov_b32_e32 v99, v0
	v_cmp_gt_u32_e64 s[4:5], s4, v154
	v_cmp_eq_u32_e64 s[6:7], 3, v104
	s_movk_i32 s34, 0x4000
	s_addc_u32 s38, s21, 0
	v_or_b32_e32 v114, 64, v113
	v_or_b32_e32 v115, 0x80, v113
	v_or_b32_e32 v116, 0xc0, v113
	s_mov_b32 s39, 0x8000
	s_movk_i32 s40, 0x2000
	s_movk_i32 s41, 0x6000
	v_add_u32_e32 v117, v9, v107
	s_mov_b32 s42, 0x30000
	s_mov_b32 s43, 0x18000
	s_mov_b32 s44, 0x48000
	s_add_i32 s46, s45, 0xf0
	s_mov_b32 s47, 0xbfb8aa3b
	s_mov_b32 s48, 0xa000
	s_mov_b32 s49, 0xc000
	s_mov_b32 s50, 0xe000
	s_mov_b32 s51, 0x10000
	s_mov_b32 s52, 0x14000
	s_mov_b32 s53, 0x16000
	s_mov_b32 s54, 0x1a000
	v_add_u32_e32 v118, v11, v1
	v_add_u32_e32 v119, v13, v6
	v_add_u32_e32 v120, v12, v7
	v_add_u32_e32 v121, v13, v18
	v_add_u32_e32 v122, v12, v17
	v_add_u32_e32 v123, v10, v8
	v_add_u32_e32 v124, v10, v19
	v_add_u32_e32 v125, v10, v20
	v_add_u32_e32 v126, v15, v21
	v_add_u32_e32 v127, v16, v22
	v_add_u32_e32 v128, v16, v14
	s_mov_b32 s22, s14
	s_branch .LBB0_2074

.LBB0_2079:
	s_or_b64 exec, exec, s[28:29]
	s_and_saveexec_b64 s[26:27], s[2:3]
	s_cbranch_execz .LBB0_2081
	s_waitcnt vmcnt(0)
	v_add_u32_e32 v251, 0xf0, v250
	ds_write2_b32 v251, v90, v91 offset1:16
	ds_write2_b32 v251, v92, v93 offset0:32 offset1:48

.LBB0_2086:
	s_and_b32 s63, s57, 1
	s_cmp_eq_u32 s63, 0
	s_cselect_b64 s[28:29], -1, 0
	s_and_b64 s[14:15], s[28:29], exec
	s_cselect_b32 s14, 0xf0, s46
	v_lshlrev_b32_e32 v135, 2, v104
	v_and_b32_e32 v155, 63, v154
	v_lshl_add_u32 v155, v155, 2, s14
	ds_read2st64_b32 v[144:145], v155 offset1:1
	ds_read2st64_b32 v[146:147], v155 offset0:4 offset1:5
	s_andn2_b64 vcc, exec, s[26:27]
	s_mov_b64 s[30:31], -1
	s_waitcnt lgkmcnt(1)
	v_mfma_f32_16x16x4_f32 v[136:139], v144, v134, 0
	v_mfma_f32_16x16x4_f32 v[136:139], v145, v133, v[136:139]
	ds_read2st64_b32 v[144:145], v155 offset0:2 offset1:3
	s_waitcnt lgkmcnt(0)
	v_mfma_f32_16x16x4_f32 v[136:139], v144, v132, v[136:139]
	v_mfma_f32_16x16x4_f32 v[140:143], v146, v134, 0
	v_mfma_f32_16x16x4_f32 v[136:139], v145, v131, v[136:139]
	ds_read2st64_b32 v[144:145], v155 offset0:6 offset1:7
	v_mfma_f32_16x16x4_f32 v[140:143], v147, v133, v[140:143]
	s_nop 7
	v_add_f32_e32 v138, v130, v138
	v_min_f32_e32 v148, 0, v138
	v_mul_f32_e64 v138, |v138|, s47
	v_exp_f32_e32 v138, v138
	v_add_f32_e32 v139, v130, v139
	v_mul_f32_e64 v149, |v139|, s47
	v_exp_f32_e32 v149, v149
	s_waitcnt lgkmcnt(0)
	v_mfma_f32_16x16x4_f32 v[140:143], v144, v132, v[140:143]
	v_add_f32_e32 v138, 1.0, v138
	v_log_f32_e32 v138, v138
	v_add_f32_e32 v136, v130, v136
	v_add_f32_e32 v137, v130, v137
	v_min_f32_e32 v146, 0, v136
	v_mul_f32_e64 v136, |v136|, s47
	v_min_f32_e32 v147, 0, v137
	v_mfma_f32_16x16x4_f32 v[140:143], v145, v131, v[140:143]
	v_mul_f32_e64 v137, |v137|, s47
	v_exp_f32_e32 v136, v136
	v_exp_f32_e32 v137, v137
	v_add_f32_e32 v149, 1.0, v149
	v_fmac_f32_e32 v148, 0xbf317218, v138
	v_log_f32_e32 v144, v149
	v_mul_f32_e32 v138, 0x3d800000, v148
	ds_read2st64_b32 v[148:149], v155 offset0:8 offset1:9
	s_nop 1
	v_add_f32_e32 v140, v130, v140
	v_mul_f32_e64 v145, |v140|, s47
	v_add_f32_e32 v136, 1.0, v136
	v_add_f32_e32 v137, 1.0, v137
	v_exp_f32_e32 v145, v145
	v_log_f32_e32 v136, v136
	v_log_f32_e32 v137, v137
	v_min_f32_e32 v139, 0, v139
	v_fmac_f32_e32 v139, 0xbf317218, v144
	v_add_f32_e32 v144, 1.0, v145
	v_add_f32_e32 v141, v130, v141
	v_fmac_f32_e32 v146, 0xbf317218, v136
	v_fmac_f32_e32 v147, 0xbf317218, v137
	v_log_f32_e32 v150, v144
	v_mul_f32_e64 v144, |v141|, s47
	v_mul_f32_e32 v136, 0x3d800000, v146
	v_mul_f32_e32 v137, 0x3d800000, v147
	v_exp_f32_e32 v151, v144
	s_waitcnt lgkmcnt(0)
	v_mfma_f32_16x16x4_f32 v[144:147], v148, v134, 0
	v_min_f32_e32 v140, 0, v140
	v_fmac_f32_e32 v140, 0xbf317218, v150
	v_add_f32_e32 v148, 1.0, v151
	ds_read2st64_b32 v[150:151], v155 offset0:10 offset1:11
	v_add_f32_e32 v152, v130, v142
	v_mul_f32_e64 v142, |v152|, s47
	v_exp_f32_e32 v142, v142
	v_mfma_f32_16x16x4_f32 v[144:147], v149, v133, v[144:147]
	v_log_f32_e32 v148, v148
	v_min_f32_e32 v141, 0, v141
	v_add_f32_e32 v142, 1.0, v142
	v_add_f32_e32 v149, v130, v143
	v_fmac_f32_e32 v141, 0xbf317218, v148
	v_log_f32_e32 v148, v142
	v_mul_f32_e32 v139, 0x3d800000, v139
	s_waitcnt lgkmcnt(0)
	v_mfma_f32_16x16x4_f32 v[142:145], v150, v132, v[144:147]
	s_nop 0
	v_mul_f32_e64 v146, |v149|, s47
	v_exp_f32_e32 v146, v146
	v_min_f32_e32 v150, 0, v152
	v_fmac_f32_e32 v150, 0xbf317218, v148
	ds_read2st64_b32 v[152:153], v155 offset0:12 offset1:13
	v_add_f32_e32 v146, 1.0, v146
	v_log_f32_e32 v148, v146
	v_mfma_f32_16x16x4_f32 v[144:147], v151, v131, v[142:145]
	v_min_f32_e32 v149, 0, v149
	v_mul_f32_e32 v140, 0x3d800000, v140
	v_fmac_f32_e32 v149, 0xbf317218, v148
	v_mul_f32_e32 v141, 0x3d800000, v141
	s_nop 5
	v_add_f32_e32 v144, v130, v144
	v_mul_f32_e64 v142, |v144|, s47
	v_exp_f32_e32 v143, v142
	v_add_f32_e32 v145, v130, v145
	v_mul_f32_e32 v142, 0x3d800000, v150
	v_min_f32_e32 v144, 0, v144
	v_add_f32_e32 v143, 1.0, v143
	v_log_f32_e32 v148, v143
	v_mul_f32_e64 v143, |v145|, s47
	v_exp_f32_e32 v150, v143
	v_mul_f32_e32 v143, 0x3d800000, v149
	v_fmac_f32_e32 v144, 0xbf317218, v148
	v_min_f32_e32 v145, 0, v145
	v_add_f32_e32 v148, 1.0, v150
	v_log_f32_e32 v156, v148
	s_waitcnt lgkmcnt(0)
	v_mfma_f32_16x16x4_f32 v[148:151], v152, v134, 0
	v_add_f32_e32 v146, v130, v146
	v_min_f32_e32 v152, 0, v146
	v_fmac_f32_e32 v145, 0xbf317218, v156
	ds_read2st64_b32 v[156:157], v155 offset0:14 offset1:15
	v_mul_f32_e64 v146, |v146|, s47
	v_exp_f32_e32 v146, v146
	v_mul_f32_e32 v144, 0x3d800000, v144
	v_mfma_f32_16x16x4_f32 v[148:151], v153, v133, v[148:151]
	v_add_f32_e32 v153, v130, v147
	v_mul_f32_e64 v147, |v153|, s47
	v_add_f32_e32 v146, 1.0, v146
	v_exp_f32_e32 v155, v147
	v_log_f32_e32 v158, v146
	v_mul_f32_e32 v145, 0x3d800000, v145
	v_fmac_f32_e32 v152, 0xbf317218, v158
	s_waitcnt lgkmcnt(0)
	v_mfma_f32_16x16x4_f32 v[146:149], v156, v132, v[148:151]
	s_nop 0
	v_add_f32_e32 v150, 1.0, v155
	v_log_f32_e32 v150, v150
	v_min_f32_e32 v151, 0, v153
	v_mul_f32_e32 v163, 0x3d800000, v152
	v_fmac_f32_e32 v151, 0xbf317218, v150
	v_mul_f32_e32 v164, 0x3d800000, v151
	v_mfma_f32_16x16x4_f32 v[146:149], v157, v131, v[146:149]
	s_nop 9
	v_add_f32_e32 v146, v130, v146
	v_mul_f32_e64 v150, |v146|, s47
	v_exp_f32_e32 v150, v150
	v_add_f32_e32 v147, v130, v147
	v_mul_f32_e64 v151, |v147|, s47
	v_exp_f32_e32 v151, v151
	v_add_f32_e32 v150, 1.0, v150
	v_log_f32_e32 v150, v150
	v_min_f32_e32 v146, 0, v146
	v_add_f32_e32 v151, 1.0, v151
	v_log_f32_e32 v151, v151
	v_fmac_f32_e32 v146, 0xbf317218, v150
	v_mul_f32_e32 v165, 0x3d800000, v146
	v_min_f32_e32 v146, 0, v147
	v_fmac_f32_e32 v146, 0xbf317218, v151
	v_mul_f32_e32 v166, 0x3d800000, v146
	v_add_f32_e32 v146, v130, v148
	v_mul_f32_e64 v147, |v146|, s47
	v_exp_f32_e32 v147, v147
	v_add_f32_e32 v148, v130, v149
	v_mul_f32_e64 v149, |v148|, s47
	v_exp_f32_e32 v149, v149
	v_add_f32_e32 v147, 1.0, v147
	v_log_f32_e32 v147, v147
	v_min_f32_e32 v146, 0, v146
	v_add_f32_e32 v149, 1.0, v149
	v_log_f32_e32 v149, v149
	v_fmac_f32_e32 v146, 0xbf317218, v147
	v_mul_f32_e32 v167, 0x3d800000, v146
	v_min_f32_e32 v146, 0, v148
	v_fmac_f32_e32 v146, 0xbf317218, v149
	v_mul_f32_e32 v168, 0x3d800000, v146
	v_cndmask_b32_e64 v146, 0, 1, s[26:27]
	v_cmp_ne_u32_e64 s[14:15], 1, v146
	s_cbranch_vccnz .LBB0_2088
	v_add_f32_e32 v146, 0, v168
	v_add_f32_e32 v147, v167, v146
	v_add_f32_e32 v148, v166, v147
	v_add_f32_e32 v149, v165, v148
	v_add_f32_e32 v150, v164, v149
	v_add_f32_e32 v151, v163, v150
	v_add_f32_e32 v152, v145, v151
	v_add_f32_e32 v153, v144, v152
	v_add_f32_e32 v155, v143, v153
	v_add_f32_e32 v156, v142, v155
	v_add_f32_e32 v157, v141, v156
	v_add_f32_e32 v158, v140, v157
	v_add_f32_e32 v159, v139, v158
	v_add_f32_e32 v160, v138, v159
	v_add_f32_e32 v161, v137, v160
	v_add_f32_e32 v162, v136, v161
	s_mov_b64 s[30:31], 0

.LBB0_2098:
	s_and_b64 s[28:29], s[28:29], exec
	s_cselect_b32 s28, s46, 0xf0
	v_add_u32_e32 v136, s28, v250
	ds_write2_b32 v136, v90, v91 offset1:16
	ds_write2_b32 v136, v92, v93 offset0:32 offset1:48
	s_or_b64 exec, exec, s[30:31]
	s_cmp_ge_u32 s57, s55
	s_cbranch_scc1 .LBB0_2085

.LBB0_2101:
	v_and_b32_e32 v148, 63, v154
	v_lshl_add_u32 v148, v148, 2, s46
	ds_read2st64_b32 v[136:137], v148 offset1:1
	ds_read2st64_b32 v[140:141], v148 offset0:2 offset1:3
	ds_read2st64_b32 v[142:143], v148 offset0:4 offset1:5
	ds_read2st64_b32 v[144:145], v148 offset0:6 offset1:7
	s_and_b64 vcc, exec, s[14:15]
	s_mov_b64 s[24:25], -1
	s_waitcnt lgkmcnt(3)
	v_mfma_f32_16x16x4_f32 v[90:93], v136, v134, 0
	v_mfma_f32_16x16x4_f32 v[90:93], v137, v133, v[90:93]
	s_waitcnt lgkmcnt(2)
	v_mfma_f32_16x16x4_f32 v[90:93], v140, v132, v[90:93]
	s_waitcnt lgkmcnt(1)
	v_mfma_f32_16x16x4_f32 v[136:139], v142, v134, 0
	v_mfma_f32_16x16x4_f32 v[90:93], v141, v131, v[90:93]
	v_mfma_f32_16x16x4_f32 v[136:139], v143, v133, v[136:139]
	s_nop 8
	v_add_f32_e32 v90, v130, v90
	v_min_f32_e32 v135, 0, v90
	v_mul_f32_e64 v90, |v90|, s47
	v_exp_f32_e32 v90, v90
	v_add_f32_e32 v91, v130, v91
	v_min_f32_e32 v140, 0, v91
	v_mul_f32_e64 v91, |v91|, s47
	s_waitcnt lgkmcnt(0)
	v_mfma_f32_16x16x4_f32 v[136:139], v144, v132, v[136:139]
	v_add_f32_e32 v90, 1.0, v90
	v_exp_f32_e32 v91, v91
	v_log_f32_e32 v90, v90
	v_add_f32_e32 v92, v130, v92
	v_add_f32_e32 v93, v130, v93
	v_add_f32_e32 v91, 1.0, v91
	v_fmac_f32_e32 v135, 0xbf317218, v90
	v_mfma_f32_16x16x4_f32 v[136:139], v145, v131, v[136:139]
	v_mul_f32_e64 v141, |v92|, s47
	v_log_f32_e32 v91, v91
	v_mul_f32_e32 v90, 0x3d800000, v135
	v_mul_f32_e64 v135, |v93|, s47
	v_exp_f32_e32 v141, v141
	v_exp_f32_e32 v135, v135
	ds_read2st64_b32 v[144:145], v148 offset0:8 offset1:9
	v_fmac_f32_e32 v140, 0xbf317218, v91
	s_nop 1
	v_add_f32_e32 v136, v130, v136
	v_add_f32_e32 v141, 1.0, v141
	v_mul_f32_e32 v91, 0x3d800000, v140
	v_add_f32_e32 v135, 1.0, v135
	v_mul_f32_e64 v140, |v136|, s47
	v_log_f32_e32 v141, v141
	v_log_f32_e32 v135, v135
	v_exp_f32_e32 v140, v140
	v_min_f32_e32 v92, 0, v92
	v_min_f32_e32 v93, 0, v93
	v_fmac_f32_e32 v92, 0xbf317218, v141
	v_fmac_f32_e32 v93, 0xbf317218, v135
	v_add_f32_e32 v135, 1.0, v140
	s_waitcnt lgkmcnt(0)
	v_mfma_f32_16x16x4_f32 v[140:143], v144, v134, 0
	v_add_f32_e32 v146, v130, v137
	v_mul_f32_e64 v137, |v146|, s47
	v_log_f32_e32 v135, v135
	v_exp_f32_e32 v137, v137
	v_min_f32_e32 v144, 0, v136
	v_add_f32_e32 v149, v130, v138
	v_fmac_f32_e32 v144, 0xbf317218, v135
	v_add_f32_e32 v135, 1.0, v137
	ds_read2st64_b32 v[136:137], v148 offset0:10 offset1:11
	v_mfma_f32_16x16x4_f32 v[140:143], v145, v133, v[140:143]
	v_log_f32_e32 v147, v135
	v_mul_f32_e64 v135, |v149|, s47
	v_exp_f32_e32 v138, v135
	v_mul_f32_e32 v135, 0x3d800000, v144
	v_min_f32_e32 v144, 0, v146
	v_add_f32_e32 v146, v130, v139
	v_add_f32_e32 v138, 1.0, v138
	v_log_f32_e32 v145, v138
	s_waitcnt lgkmcnt(0)
	v_mfma_f32_16x16x4_f32 v[138:141], v136, v132, v[140:143]
	v_mul_f32_e64 v136, |v146|, s47
	v_exp_f32_e32 v142, v136
	v_fmac_f32_e32 v144, 0xbf317218, v147
	v_mul_f32_e32 v136, 0x3d800000, v144
	v_min_f32_e32 v143, 0, v149
	v_add_f32_e32 v142, 1.0, v142
	v_fmac_f32_e32 v143, 0xbf317218, v145
	v_mfma_f32_16x16x4_f32 v[138:141], v137, v131, v[138:141]
	v_log_f32_e32 v142, v142
	v_mul_f32_e32 v92, 0x3d800000, v92
	v_mul_f32_e32 v93, 0x3d800000, v93
	s_nop 6
	v_add_f32_e32 v144, v130, v138
	v_mul_f32_e64 v137, |v144|, s47
	v_exp_f32_e32 v138, v137
	v_mul_f32_e32 v137, 0x3d800000, v143
	v_min_f32_e32 v143, 0, v146
	ds_read2st64_b32 v[146:147], v148 offset0:12 offset1:13
	v_add_f32_e32 v138, 1.0, v138
	v_add_f32_e32 v139, v130, v139
	v_fmac_f32_e32 v143, 0xbf317218, v142
	v_log_f32_e32 v142, v138
	v_mul_f32_e64 v138, |v139|, s47
	v_exp_f32_e32 v145, v138
	v_min_f32_e32 v149, 0, v144
	v_fmac_f32_e32 v149, 0xbf317218, v142
	v_mul_f32_e32 v138, 0x3d800000, v143
	v_add_f32_e32 v142, 1.0, v145
	v_log_f32_e32 v150, v142
	s_waitcnt lgkmcnt(0)
	v_mfma_f32_16x16x4_f32 v[142:145], v146, v134, 0
	v_mul_f32_e32 v134, 0x3d800000, v149
	ds_read2st64_b32 v[148:149], v148 offset0:14 offset1:15
	v_add_f32_e32 v140, v130, v140
	v_min_f32_e32 v139, 0, v139
	v_min_f32_e32 v146, 0, v140
	v_fmac_f32_e32 v139, 0xbf317218, v150
	v_mul_f32_e32 v139, 0x3d800000, v139
	v_mfma_f32_16x16x4_f32 v[142:145], v147, v133, v[142:145]
	v_add_f32_e32 v147, v130, v141
	v_mul_f32_e64 v133, |v140|, s47
	v_mul_f32_e64 v140, |v147|, s47
	v_exp_f32_e32 v150, v140
	v_exp_f32_e32 v133, v133
	s_nop 0
	v_add_f32_e32 v133, 1.0, v133
	s_waitcnt lgkmcnt(0)
	v_mfma_f32_16x16x4_f32 v[140:143], v148, v132, v[142:145]
	v_log_f32_e32 v133, v133
	v_add_f32_e32 v132, 1.0, v150
	v_log_f32_e32 v132, v132
	v_fmac_f32_e32 v146, 0xbf317218, v133
	v_min_f32_e32 v133, 0, v147
	v_fmac_f32_e32 v133, 0xbf317218, v132
	v_mfma_f32_16x16x4_f32 v[140:143], v149, v131, v[140:143]
	v_mul_f32_e32 v153, 0x3d800000, v133
	v_mul_f32_e32 v152, 0x3d800000, v146
	s_nop 7
	v_add_f32_e32 v131, v130, v140
	v_mul_f32_e64 v132, |v131|, s47
	v_exp_f32_e32 v132, v132
	v_add_f32_e32 v133, v130, v141
	v_mul_f32_e64 v140, |v133|, s47
	v_exp_f32_e32 v140, v140
	v_add_f32_e32 v132, 1.0, v132
	v_log_f32_e32 v132, v132
	v_min_f32_e32 v131, 0, v131
	v_add_f32_e32 v140, 1.0, v140
	v_log_f32_e32 v140, v140
	v_fmac_f32_e32 v131, 0xbf317218, v132
	v_mul_f32_e32 v155, 0x3d800000, v131
	v_min_f32_e32 v131, 0, v133
	v_fmac_f32_e32 v131, 0xbf317218, v140
	v_mul_f32_e32 v156, 0x3d800000, v131
	v_add_f32_e32 v131, v130, v142
	v_add_f32_e32 v130, v130, v143
	v_mul_f32_e64 v132, |v131|, s47
	v_mul_f32_e64 v133, |v130|, s47
	v_exp_f32_e32 v132, v132
	v_exp_f32_e32 v133, v133
	v_min_f32_e32 v131, 0, v131
	v_min_f32_e32 v130, 0, v130
	v_add_f32_e32 v132, 1.0, v132
	v_add_f32_e32 v133, 1.0, v133
	v_log_f32_e32 v132, v132
	v_log_f32_e32 v133, v133
	v_fmac_f32_e32 v131, 0xbf317218, v132
	v_fmac_f32_e32 v130, 0xbf317218, v133
	v_mul_f32_e32 v157, 0x3d800000, v131
	v_mul_f32_e32 v158, 0x3d800000, v130
	s_cbranch_vccnz .LBB0_2103
	v_add_f32_e32 v130, 0, v158
	v_add_f32_e32 v131, v157, v130
	v_add_f32_e32 v132, v156, v131
	v_add_f32_e32 v133, v155, v132
	v_add_f32_e32 v140, v153, v133
	v_add_f32_e32 v141, v152, v140
	v_add_f32_e32 v142, v139, v141
	v_add_f32_e32 v143, v134, v142
	v_add_f32_e32 v144, v138, v143
	v_add_f32_e32 v145, v137, v144
	v_add_f32_e32 v146, v136, v145
	v_add_f32_e32 v147, v135, v146
	v_add_f32_e32 v148, v93, v147
	v_add_f32_e32 v149, v92, v148
	v_add_f32_e32 v150, v91, v149
	v_add_f32_e32 v151, v90, v150
	s_mov_b64 s[24:25], 0

.LBB0_2169:
	v_lshrrev_b32_e32 v250, 6, v154
	v_bfe_u32 v251, v154, 2, 2
	v_lshlrev_b32_e32 v250, 4, v250
	v_lshl_add_u32 v250, v251, 2, v250
	v_and_b32_e32 v251, 3, v154
	v_lshl_add_u32 v250, v251, 8, v250
	v_bfe_u32 v251, v154, 4, 2
	v_lshl_add_u32 v250, v251, 10, v250
	v_mov_b32_e32 v4, 0
	ds_read_b128 v[0:3], v4 offset:80
	ds_read2_b64 v[4:7], v4 offset0:12 offset1:27
	v_readlane_b32 s4, v240, 0
	s_cmp_gt_i32 s4, -1
	s_mov_b64 s[4:5], -1
	s_waitcnt lgkmcnt(0)
	v_readfirstlane_b32 s3, v1
	v_readfirstlane_b32 s2, v0
	v_readfirstlane_b32 s1, v3
	v_readfirstlane_b32 s0, v2
	v_readfirstlane_b32 s28, v5
	v_readfirstlane_b32 s29, v4
	v_readfirstlane_b32 s37, v7
	v_readfirstlane_b32 s39, v6
	s_cbranch_scc0 .LBB0_2174
	v_readlane_b32 s4, v240, 0
	s_mov_b32 s12, 0x40000
	s_nop 0
	v_lshl_add_u32 v2, s4, 9, v154
	v_cmp_gt_u32_e32 vcc, s12, v2
	s_and_saveexec_b64 s[4:5], vcc
	s_cbranch_execz .LBB0_2173
	s_add_u32 s6, s39, 0x6b20000
	s_addc_u32 s7, s37, 0
	s_add_u32 s8, s39, 0xab20000
	s_addc_u32 s9, s37, 0
	s_lshl_b32 s13, s66, 9
	s_mov_b64 s[10:11], 0
	v_mov_b32_e32 v1, 0
	s_movk_i32 s14, 0x1000
	s_mov_b32 s15, 0x3ffff

.LBB0_2183:
	s_add_u32 s0, s48, s34
	s_addc_u32 s1, s49, s35
	s_add_u32 s58, s39, s34
	s_addc_u32 s59, s37, s35
	s_add_u32 s42, s58, s44
	s_addc_u32 s43, s59, 0
	s_add_u32 s60, s42, 0x16e40800
	s_addc_u32 s61, s43, 0
	s_and_b32 s57, s56, 1
	s_cmp_eq_u32 s57, 0
	s_cselect_b64 s[42:43], -1, 0
	s_and_b64 s[62:63], s[42:43], exec
	s_cselect_b32 s62, 0xf0, s52
	v_and_b32_e32 v136, 63, v154
	v_lshl_add_u32 v136, v136, 2, s62
	ds_read2st64_b32 v[72:73], v136 offset1:1
	v_lshl_add_u64 v[74:75], s[0:1], 0, v[102:103]
	ds_read2st64_b32 v[80:81], v136 offset0:4 offset1:5
	global_load_dwordx4 v[92:95], v[74:75], off
	global_load_dwordx4 v[96:99], v[74:75], off offset:1024
	ds_read2st64_b32 v[132:133], v136 offset0:2 offset1:3
	v_lshl_add_u64 v[82:83], s[60:61], 0, v[104:105]
	s_waitcnt lgkmcnt(2)
	v_mfma_f32_16x16x4_f32 v[68:71], v72, v155, 0
	v_add_co_u32_e64 v72, s[0:1], s50, v74
	v_mfma_f32_16x16x4_f32 v[68:71], v73, v164, v[68:71]
	s_nop 0
	v_addc_co_u32_e64 v73, s[0:1], 0, v75, s[0:1]
	global_load_dwordx4 v[84:87], v[72:73], off
	global_load_dwordx4 v[88:91], v[72:73], off offset:1024
	v_add_co_u32_e64 v72, s[0:1], s45, v82
	s_nop 1
	v_addc_co_u32_e64 v73, s[0:1], 0, v83, s[0:1]
	s_waitcnt lgkmcnt(0)
	v_mfma_f32_16x16x4_f32 v[124:127], v132, v165, v[68:71]
	v_add_co_u32_e64 v134, s[0:1], s50, v82
	global_load_dwordx4 v[68:71], v[82:83], off
	s_nop 0
	global_load_dwordx4 v[72:75], v[72:73], off
	v_addc_co_u32_e64 v135, s[0:1], 0, v83, s[0:1]
	v_mfma_f32_16x16x4_f32 v[76:79], v80, v155, 0
	v_add_co_u32_e64 v80, s[0:1], s51, v82
	v_mfma_f32_16x16x4_f32 v[124:127], v133, v166, v[124:127]
	v_mfma_f32_16x16x4_f32 v[128:131], v81, v164, v[76:79]
	v_addc_co_u32_e64 v81, s[0:1], 0, v83, s[0:1]
	s_nop 5
	global_load_dwordx4 v[76:79], v[134:135], off
	s_nop 0
	global_load_dwordx4 v[80:83], v[80:81], off
	ds_read2st64_b32 v[134:135], v136 offset0:6 offset1:7
	v_add_f32_e32 v124, v167, v124
	v_min_f32_e32 v137, 0, v124
	v_mul_f32_e64 v124, |v124|, s53
	v_exp_f32_e32 v124, v124
	v_add_f32_e32 v126, v167, v126
	v_mul_f32_e64 v133, |v126|, s53
	v_exp_f32_e32 v133, v133
	v_add_f32_e32 v124, 1.0, v124
	v_log_f32_e32 v124, v124
	s_waitcnt lgkmcnt(0)
	v_mfma_f32_16x16x4_f32 v[128:131], v134, v165, v[128:131]
	v_add_f32_e32 v133, 1.0, v133
	v_min_f32_e32 v139, 0, v126
	v_fmac_f32_e32 v137, 0xbf317218, v124
	v_log_f32_e32 v124, v133
	v_add_f32_e32 v134, v167, v127
	v_add_f32_e32 v125, v167, v125
	v_mul_f32_e64 v132, |v125|, s53
	v_fmac_f32_e32 v139, 0xbf317218, v124
	v_mul_f32_e64 v124, |v134|, s53
	v_min_f32_e32 v138, 0, v125
	v_exp_f32_e32 v140, v124
	v_mfma_f32_16x16x4_f32 v[124:127], v135, v166, v[128:131]
	v_exp_f32_e32 v132, v132
	v_add_f32_e32 v129, 1.0, v140
	v_log_f32_e32 v129, v129
	v_add_f32_e32 v132, 1.0, v132
	v_log_f32_e32 v132, v132
	v_min_f32_e32 v140, 0, v134
	s_nop 3
	v_add_f32_e32 v124, v167, v124
	v_mul_f32_e64 v128, |v124|, s53
	v_fmac_f32_e32 v138, 0xbf317218, v132
	v_exp_f32_e32 v128, v128
	ds_read2st64_b32 v[132:133], v136 offset0:8 offset1:9
	v_min_f32_e32 v141, 0, v124
	v_fmac_f32_e32 v140, 0xbf317218, v129
	v_add_f32_e32 v128, 1.0, v128
	v_log_f32_e32 v128, v128
	ds_read2st64_b32 v[134:135], v136 offset0:10 offset1:11
	v_add_f32_e32 v124, v167, v125
	v_mul_f32_e64 v125, |v124|, s53
	v_fmac_f32_e32 v141, 0xbf317218, v128
	s_waitcnt lgkmcnt(1)
	v_mfma_f32_16x16x4_f32 v[128:131], v132, v155, 0
	v_add_f32_e32 v132, v167, v126
	v_exp_f32_e32 v125, v125
	v_mul_f32_e64 v126, |v132|, s53
	v_exp_f32_e32 v126, v126
	v_min_f32_e32 v142, 0, v124
	v_add_f32_e32 v124, 1.0, v125
	v_add_f32_e32 v144, v167, v127
	v_mfma_f32_16x16x4_f32 v[128:131], v133, v164, v[128:131]
	v_log_f32_e32 v133, v124
	v_add_f32_e32 v124, 1.0, v126
	v_log_f32_e32 v143, v124
	v_mul_f32_e64 v145, |v144|, s53
	v_fmac_f32_e32 v142, 0xbf317218, v133
	s_waitcnt lgkmcnt(0)
	v_mfma_f32_16x16x4_f32 v[124:127], v134, v165, v[128:131]
	s_nop 2
	v_exp_f32_e32 v128, v145
	v_min_f32_e32 v145, 0, v132
	ds_read2st64_b32 v[132:133], v136 offset0:12 offset1:13
	v_fmac_f32_e32 v145, 0xbf317218, v143
	v_add_f32_e32 v128, 1.0, v128
	v_log_f32_e32 v128, v128
	v_min_f32_e32 v143, 0, v144
	v_mfma_f32_16x16x4_f32 v[124:127], v135, v166, v[124:127]
	v_fmac_f32_e32 v143, 0xbf317218, v128
	s_nop 8
	v_add_f32_e32 v124, v167, v124
	v_mul_f32_e64 v128, |v124|, s53
	v_exp_f32_e32 v134, v128
	s_waitcnt lgkmcnt(0)
	v_mfma_f32_16x16x4_f32 v[128:131], v132, v155, 0
	v_add_f32_e32 v125, v167, v125
	v_mul_f32_e64 v135, |v125|, s53
	v_exp_f32_e32 v132, v135
	v_min_f32_e32 v144, 0, v124
	v_add_f32_e32 v124, 1.0, v134
	ds_read2st64_b32 v[134:135], v136 offset0:14 offset1:15
	v_add_f32_e32 v132, 1.0, v132
	v_mfma_f32_16x16x4_f32 v[128:131], v133, v164, v[128:131]
	v_log_f32_e32 v132, v132
	v_log_f32_e32 v124, v124
	v_min_f32_e32 v133, 0, v125
	v_add_f32_e32 v146, v167, v127
	v_fmac_f32_e32 v133, 0xbf317218, v132
	v_add_f32_e32 v132, v167, v126
	v_fmac_f32_e32 v144, 0xbf317218, v124
	v_mul_f32_e64 v124, |v132|, s53
	v_exp_f32_e32 v136, v124
	s_waitcnt lgkmcnt(0)
	v_mfma_f32_16x16x4_f32 v[124:127], v134, v165, v[128:131]
	v_mul_f32_e64 v128, |v146|, s53
	v_exp_f32_e32 v128, v128
	v_add_f32_e32 v130, 1.0, v136
	v_log_f32_e32 v130, v130
	v_min_f32_e32 v129, 0, v132
	v_add_f32_e32 v128, 1.0, v128
	v_log_f32_e32 v128, v128
	v_mfma_f32_16x16x4_f32 v[124:127], v135, v166, v[124:127]
	v_fmac_f32_e32 v129, 0xbf317218, v130
	v_min_f32_e32 v130, 0, v146
	v_fmac_f32_e32 v130, 0xbf317218, v128
	s_nop 6
	v_add_f32_e32 v124, v167, v124
	v_mul_f32_e64 v131, |v124|, s53
	v_exp_f32_e32 v131, v131
	v_add_f32_e32 v125, v167, v125
	v_min_f32_e32 v124, 0, v124
	v_add_f32_e32 v126, v167, v126
	v_add_f32_e32 v128, 1.0, v131
	v_mul_f32_e64 v131, |v125|, s53
	v_log_f32_e32 v128, v128
	v_exp_f32_e32 v131, v131
	v_add_f32_e32 v127, v167, v127
	v_mul_f32_e64 v132, |v127|, s53
	v_fmac_f32_e32 v124, 0xbf317218, v128
	v_add_f32_e32 v128, 1.0, v131
	v_mul_f32_e64 v131, |v126|, s53
	v_log_f32_e32 v128, v128
	v_exp_f32_e32 v131, v131
	v_exp_f32_e32 v132, v132
	v_min_f32_e32 v125, 0, v125
	v_fmac_f32_e32 v125, 0xbf317218, v128
	v_add_f32_e32 v128, 1.0, v131
	v_add_f32_e32 v131, 1.0, v132
	v_log_f32_e32 v131, v131
	v_log_f32_e32 v128, v128
	v_min_f32_e32 v127, 0, v127
	v_min_f32_e32 v126, 0, v126
	v_fmac_f32_e32 v127, 0xbf317218, v131
	v_fmac_f32_e32 v126, 0xbf317218, v128
	v_fma_f32 v127, v127, s54, 0
	v_fmamk_f32 v126, v126, 0x3d800000, v127
	v_fmamk_f32 v125, v125, 0x3d800000, v126
	v_fmamk_f32 v124, v124, 0x3d800000, v125
	v_fmamk_f32 v128, v130, 0x3d800000, v124
	v_fmamk_f32 v129, v129, 0x3d800000, v128
	v_fmamk_f32 v130, v133, 0x3d800000, v129
	v_fmamk_f32 v131, v144, 0x3d800000, v130
	v_fmamk_f32 v132, v143, 0x3d800000, v131
	v_fmamk_f32 v133, v145, 0x3d800000, v132
	v_fmamk_f32 v134, v142, 0x3d800000, v133
	v_fmamk_f32 v135, v141, 0x3d800000, v134
	v_fmamk_f32 v136, v140, 0x3d800000, v135
	v_fmamk_f32 v139, v139, 0x3d800000, v136
	v_fmamk_f32 v138, v138, 0x3d800000, v139
	v_fmamk_f32 v137, v137, 0x3d800000, v138
	ds_bpermute_b32 v140, v174, v137
	ds_bpermute_b32 v141, v173, v137
	ds_bpermute_b32 v142, v172, v137
	s_waitcnt lgkmcnt(2)
	v_cndmask_b32_e64 v140, v140, 0, s[2:3]
	s_waitcnt lgkmcnt(1)
	v_cndmask_b32_e64 v141, 0, v141, s[4:5]
	v_add_f32_e32 v140, v141, v140
	s_waitcnt lgkmcnt(0)
	v_cndmask_b32_e64 v141, 0, v142, s[6:7]
	v_add_f32_e32 v140, v141, v140
	v_add_f32_e32 v137, v140, v137
	v_add_f32_e32 v138, v140, v138
	v_add_f32_e32 v124, v140, v124
	v_add_f32_e32 v125, v140, v125
	ds_write2st64_b32 v184, v137, v138 offset0:24 offset1:26
	v_add_f32_e32 v137, v140, v139
	v_add_f32_e32 v136, v140, v136
	v_add_f32_e32 v135, v140, v135
	v_add_f32_e32 v134, v140, v134
	v_add_f32_e32 v133, v140, v133
	v_add_f32_e32 v132, v140, v132
	v_add_f32_e32 v131, v140, v131
	v_add_f32_e32 v130, v140, v130
	v_add_f32_e32 v129, v140, v129
	v_add_f32_e32 v128, v140, v128
	ds_write2st64_b32 v184, v124, v125 offset0:48 offset1:50
	v_add_f32_e32 v124, v140, v126
	v_add_f32_e32 v125, v140, v127
	ds_write2st64_b32 v184, v137, v136 offset0:28 offset1:30
	ds_write2st64_b32 v184, v135, v134 offset0:32 offset1:34
	ds_write2st64_b32 v184, v133, v132 offset0:36 offset1:38
	ds_write2st64_b32 v184, v131, v130 offset0:40 offset1:42
	ds_write2st64_b32 v184, v129, v128 offset0:44 offset1:46
	ds_write2st64_b32 v184, v124, v125 offset0:52 offset1:54
	s_waitcnt lgkmcnt(0)
	s_barrier
	s_and_saveexec_b64 s[0:1], s[8:9]
	s_cbranch_execz .LBB0_2185
	ds_read_b32 v124, v175 offset:6144
	v_lshl_add_u32 v125, s57, 9, v175
	s_waitcnt lgkmcnt(0)
	ds_write_b32 v125, v124 offset:4096
.LBB0_2185:
	s_or_b64 exec, exec, s[0:1]
	s_cmp_gt_u32 s56, 2
	s_cbranch_scc1 .LBB0_2192
	s_and_saveexec_b64 s[0:1], vcc
	s_and_b64 s[42:43], s[42:43], exec
	s_cselect_b32 s42, s52, 0xf0
	v_add_u32_e32 v124, s42, v250
	ds_write2_b32 v124, v0, v1 offset1:16
	ds_write2_b32 v124, v2, v3 offset0:32 offset1:48
	s_or_b64 exec, exec, s[0:1]
	s_cmp_eq_u32 s34, 0xfff40000
	s_cbranch_scc1 .LBB0_2192
	s_add_u32 s42, s46, 0x2100040
	s_addc_u32 s43, s47, 0
	s_and_saveexec_b64 s[0:1], vcc
	s_cbranch_execz .LBB0_2191
	v_lshl_add_u64 v[0:1], s[42:43], 0, v[100:101]
	global_load_dwordx4 v[0:3], v[0:1], off

.LBB0_2255:
	v_lshrrev_b32_e32 v250, 6, v154
	v_bfe_u32 v251, v154, 2, 2
	v_lshlrev_b32_e32 v250, 4, v250
	v_lshl_add_u32 v250, v251, 2, v250
	v_and_b32_e32 v251, 3, v154
	v_lshl_add_u32 v250, v251, 8, v250
	v_bfe_u32 v251, v154, 4, 2
	v_lshl_add_u32 v250, v251, 10, v250
	v_mov_b32_e32 v1, 0
	ds_read_b128 v[2:5], v1 offset:80
	ds_read2_b64 v[6:9], v1 offset0:12 offset1:27
	s_waitcnt lgkmcnt(0)
	v_readfirstlane_b32 s45, v3
	v_readfirstlane_b32 s0, v7
	v_readfirstlane_b32 s44, v2
	v_readfirstlane_b32 s47, v5
	v_writelane_b32 v240, s0, 15
	v_readfirstlane_b32 s46, v4
	v_readlane_b32 s0, v240, 0
	v_readfirstlane_b32 s51, v6
	v_readfirstlane_b32 s78, v9
	s_cmpk_gt_i32 s0, 0xff
	v_readfirstlane_b32 s79, v8
	s_cbranch_scc1 .LBB0_2301
	v_and_b32_e32 v13, 3, v154
	v_lshlrev_b32_e32 v19, 2, v154
	v_and_b32_e32 v7, 15, v154
	v_lshlrev_b32_e32 v178, 4, v13
	v_lshrrev_b32_e32 v15, 4, v154
	v_and_or_b32 v13, v19, 48, v13
	v_add_u32_e32 v181, 0xf0, v19
	v_lshlrev_b32_e32 v19, 3, v154
	v_mul_u32_u24_e32 v14, 0x1800, v15
	v_lshlrev_b32_e32 v16, 4, v154
	s_movk_i32 s0, 0xf0
	v_lshlrev_b32_e32 v20, 2, v7
	v_and_b32_e32 v21, 0x3c0, v154
	v_and_b32_e32 v22, 0x78, v19
	v_mov_b32_e32 v23, 0xf0
	v_and_or_b32 v112, v16, s0, v14
	v_add3_u32 v20, s0, v21, v20
	s_movk_i32 s0, 0x80
	v_lshl_add_u32 v23, v22, 2, v23
	v_lshlrev_b32_e32 v22, 1, v22
	v_lshrrev_b32_e32 v17, 5, v154
	v_cmp_gt_u32_e64 s[10:11], s0, v154
	v_sub_u32_e32 v22, v23, v22
	s_mov_b32 s0, 0x16400
	v_lshlrev_b32_e32 v29, 9, v15
	v_mul_u32_u24_e32 v15, 0x88, v15
	v_mul_u32_u24_e32 v14, 0x1800, v17
	v_and_b32_e32 v16, 0x1f0, v16
	s_addk_i32 s0, 0xf0
	v_and_b32_e32 v19, 24, v19
	v_lshl_add_u32 v184, v15, 1, v22
	v_add_u32_e32 v15, 0x200, v154
	v_or_b32_e32 v114, v14, v16
	v_add_u32_e32 v16, s0, v16
	s_mov_b32 s12, 0x1e800
	v_add3_u32 v21, s0, v21, v19
	v_lshrrev_b32_e32 v30, 4, v15
	s_mov_b32 s0, 0x20c00
	v_bfe_u32 v9, v154, 4, 2
	v_and_b32_e32 v24, 2, v17
	s_addk_i32 s12, 0xf0
	v_lshlrev_b32_e32 v31, 9, v30
	v_mul_u32_u24_e32 v30, 0x88, v30
	s_addk_i32 s0, 0xf0
	v_lshlrev_b32_e32 v116, 2, v9
	s_movk_i32 s1, 0x100
	v_lshl_add_u32 v185, v30, 1, v22
	v_lshlrev_b32_e32 v30, 4, v24
	v_lshlrev_b32_e32 v35, 5, v24
	v_or_b32_e32 v24, 1, v24
	s_add_u32 s82, s79, 0x6b20000
	v_and_b32_e32 v3, 63, v154
	v_cmp_gt_u32_e64 s[2:3], s1, v154
	v_lshrrev_b32_e32 v25, 3, v154
	s_movk_i32 s1, 0x70
	v_or_b32_e32 v32, v30, v7
	v_or_b32_e32 v30, v30, v116
	v_lshlrev_b32_e32 v36, 4, v24
	s_addc_u32 s83, s78, 0
	v_cmp_gt_u32_e64 s[4:5], 16, v3
	v_cmp_lt_u32_e64 s[6:7], 31, v3
	v_and_or_b32 v25, v25, s1, v7
	v_or_b32_e32 v37, v36, v7
	v_or_b32_e32 v36, v36, v116
	v_cmp_gt_u32_e64 s[28:29], 32, v3
	v_or_b32_e32 v3, 1, v30
	s_add_u32 s84, s79, 0x2100000
	v_writelane_b32 v240, s48, 29
	v_lshrrev_b32_e32 v5, 6, v154
	v_cmp_lt_u32_e64 s[30:31], v3, v25
	v_or_b32_e32 v3, 1, v36
	s_addc_u32 s85, s78, 0
	v_writelane_b32 v240, s49, 30
	v_lshlrev_b32_e32 v14, 5, v5
	v_lshl_add_u32 v188, v7, 5, s0
	v_cmp_lt_u32_e64 s[38:39], v3, v25
	s_add_u32 s0, s79, 0xad20000
	v_mbcnt_lo_u32_b32 v3, -1, 0
	v_or_b32_e32 v18, v116, v14
	v_bfe_u32 v27, v154, 2, 2
	v_lshrrev_b32_e32 v28, 1, v154
	v_writelane_b32 v240, s0, 17
	s_addc_u32 s0, s78, 0
	v_mbcnt_hi_u32_b32 v3, -1, v3
	v_lshl_or_b32 v117, v5, 4, v7
	v_lshlrev_b32_e32 v18, 1, v18
	s_movk_i32 s1, 0x110
	v_and_or_b32 v27, v28, 24, v27
	v_mov_b32_e32 v44, 0x2200
	v_lshl_add_u32 v189, v5, 2, v188
	v_writelane_b32 v240, s0, 19
	s_add_u32 s0, s79, 0x2920000
	v_and_b32_e32 v5, 64, v3
	v_lshl_or_b32 v118, v7, 11, v18
	v_mul_u32_u24_e32 v40, 0x210, v27
	v_mul_u32_u24_e32 v41, 0x90, v7
	v_mul_u32_u24_e32 v42, 0x110, v7
	v_mul_u32_u24_e32 v43, 0x110, v27
	v_mad_u32_u24 v27, v27, s1, v44
	v_mul_u32_u24_e32 v44, 0x1800, v7
	v_writelane_b32 v240, s0, 21
	s_addc_u32 s0, s78, 0
	v_or_b32_e32 v7, v5, v7
	v_writelane_b32 v240, s0, 23
	s_add_u32 s0, s79, 0x17320000
	v_lshlrev_b32_e32 v190, 2, v7
	v_xor_b32_e32 v7, 16, v3
	v_add_u32_e32 v5, 64, v5
	v_writelane_b32 v240, s0, 25
	s_addc_u32 s0, s78, 0
	v_cmp_lt_i32_e32 vcc, v7, v5
	v_lshlrev_b32_e32 v11, 9, v9
	v_writelane_b32 v240, s0, 27
	v_cndmask_b32_e32 v7, v3, v7, vcc
	s_add_u32 s0, s79, 0xad20800
	v_or_b32_e32 v155, 0x4000, v11
	v_or_b32_e32 v174, 0x4800, v11
	v_or_b32_e32 v175, 0x5000, v11
	v_or_b32_e32 v176, 0x5800, v11
	v_lshrrev_b32_e32 v11, 2, v154
	v_lshlrev_b32_e32 v180, 6, v13
	v_and_b32_e32 v13, 48, v154
	v_add_u32_e32 v22, 0x600, v154
	v_lshlrev_b32_e32 v194, 2, v7
	v_xor_b32_e32 v7, 32, v3
	v_writelane_b32 v240, s0, 13
	s_addc_u32 s0, s78, 0
	v_lshlrev_b32_e32 v179, 6, v11
	v_cmp_eq_u32_e64 s[8:9], 3, v9
	v_lshlrev_b32_e32 v9, 3, v9
	v_add_u32_e32 v182, 0xf0, v13
	v_mul_u32_u24_e32 v26, 0x90, v25
	v_lshrrev_b32_e32 v15, 5, v15
	v_lshrrev_b32_e32 v22, 5, v22
	v_cmp_lt_i32_e32 vcc, v7, v5
	v_writelane_b32 v240, s0, 31
	v_or_b32_e32 v0, 0x400, v154
	v_or_b32_e32 v2, 0x800, v154
	v_or_b32_e32 v4, 0xc00, v154
	v_or_b32_e32 v6, 0x1000, v154
	v_or_b32_e32 v8, 0x1400, v154
	v_or_b32_e32 v10, 0x1800, v154
	v_or_b32_e32 v12, 0x1c00, v154
	v_lshl_or_b32 v110, v11, 7, v178
	v_add_u32_e32 v11, 0xf0, v179
	v_add3_u32 v26, s12, v26, v9
	v_add_u32_e32 v28, s12, v13
	v_sub_u32_e32 v9, v182, v9
	v_add_u32_e32 v19, 0xf0, v19
	v_lshlrev_b32_e32 v13, 9, v13
	v_mul_u32_u24_e32 v17, 0x210, v17
	v_mul_u32_u24_e32 v15, 0x210, v15
	v_mul_u32_u24_e32 v22, 0x210, v22
	v_mul_u32_u24_e32 v32, 0x110, v32
	v_or_b32_e32 v33, 2, v30
	v_or_b32_e32 v34, 3, v30
	v_mul_u32_u24_e32 v37, 0x110, v37
	v_or_b32_e32 v38, 2, v36
	v_or_b32_e32 v39, 3, v36
	v_lshlrev_b32_e32 v24, 5, v24
	v_cndmask_b32_e32 v3, v3, v7, vcc
	v_readlane_b32 s97, v240, 0
	v_or_b32_e32 v177, 0x400, v117
	v_mov_b32_e32 v111, v1
	v_mad_u32_u24 v183, v25, s1, v182
	v_mov_b32_e32 v113, v1
	v_mov_b32_e32 v115, v1
	v_cmp_gt_u32_e64 s[12:13], v30, v25
	v_cmp_lt_u32_e64 s[14:15], v30, v25
	v_cmp_gt_u32_e64 s[16:17], v33, v25
	v_cmp_gt_u32_e64 s[18:19], v34, v25
	v_cmp_gt_u32_e64 s[20:21], v36, v25
	v_cmp_lt_u32_e64 s[22:23], v36, v25
	v_cmp_gt_u32_e64 s[24:25], v38, v25
	v_cmp_gt_u32_e64 s[26:27], v39, v25
	v_mov_b32_e32 v119, v1
	v_or_b32_e32 v186, 0x2000, v117
	v_or_b32_e32 v187, 0x600, v117
	v_or_b32_e32 v120, v18, v44
	v_or_b32_e32 v122, 0x8000, v118
	v_mov_b32_e32 v123, v1
	v_or_b32_e32 v124, 0x8020, v118
	v_mov_b32_e32 v125, v1
	v_or_b32_e32 v126, 0x10000, v118
	v_mov_b32_e32 v127, v1
	v_or_b32_e32 v128, 0x10020, v118
	v_mov_b32_e32 v129, v1
	s_mov_b32 s81, 0x18000
	v_or_b32_e32 v130, 0x18000, v118
	v_mov_b32_e32 v131, v1
	v_or_b32_e32 v132, 0x18020, v118
	v_mov_b32_e32 v133, v1
	v_cmp_lt_u32_e64 s[34:35], v33, v25
	v_cmp_lt_u32_e64 s[36:37], v34, v25
	v_cmp_lt_u32_e64 s[40:41], v38, v25
	v_cmp_lt_u32_e64 s[42:43], v39, v25
	v_mov_b32_e32 v121, v1
	s_mov_b32 s93, 0
	v_or_b32_e32 v191, 64, v190
	v_or_b32_e32 v192, 0x80, v190
	v_or_b32_e32 v193, 0xc0, v190
	v_lshlrev_b32_e32 v195, 2, v3
	v_lshlrev_b32_e32 v196, 4, v0
	v_lshlrev_b32_e32 v197, 4, v2
	v_lshlrev_b32_e32 v198, 4, v4
	v_lshlrev_b32_e32 v199, 4, v6
	s_mov_b32 s1, 0x12000
	v_lshlrev_b32_e32 v200, 4, v8
	v_lshlrev_b32_e32 v201, 4, v10
	v_lshlrev_b32_e32 v202, 4, v12
	s_mov_b32 s72, 0x30000
	s_mov_b32 s73, 0x48000
	s_mov_b32 s66, 0xbfb8aa3b
	s_mov_b32 s67, 0x3d800000
	s_mov_b32 s48, 0x3db504f3
	v_lshlrev_b32_e32 v134, 2, v14
	v_lshlrev_b32_e32 v136, 2, v116
	s_mov_b32 s50, 0x3b800000
	s_mov_b32 s80, 0x800000
	v_add_u32_e32 v203, v11, v178
	v_add_u32_e32 v204, v20, v13
	v_add_u32_e32 v205, v23, v29
	v_add_u32_e32 v206, v23, v31
	v_add_u32_e32 v207, v16, v17
	v_add_u32_e32 v208, v16, v15
	v_add_u32_e32 v209, v16, v22
	v_add_u32_e32 v210, v182, v32
	v_add_u32_e32 v211, v26, v35
	v_add_u32_e32 v212, v182, v37
	v_add_u32_e32 v213, v26, v24
	v_add_u32_e32 v214, v21, v40
	v_add_u32_e32 v215, v28, v41
	v_add_u32_e32 v216, v9, v42
	v_add_u32_e32 v217, v19, v43
	v_add_u32_e32 v218, v19, v27
	s_mov_b32 s96, s97
	s_branch .LBB0_2258

.LBB0_2260:
	s_or_b64 exec, exec, s[56:57]
	s_and_saveexec_b64 s[54:55], s[2:3]
	s_cbranch_execz .LBB0_2262
	s_waitcnt vmcnt(0)
	v_add_u32_e32 v251, 0xf0, v250
	ds_write2_b32 v251, v2, v3 offset1:16
	ds_write2_b32 v251, v4, v5 offset0:32 offset1:48

.LBB0_2267:
	s_add_u32 s62, s92, s74
	s_addc_u32 s63, s94, s75
	s_add_u32 s49, s53, s74
	s_addc_u32 s61, s55, s75
	v_lshl_add_u64 v[70:71], s[62:63], 0, v[112:113]
	s_add_u32 s62, s49, s0
	v_add_co_u32_e32 v74, vcc, s72, v70
	s_addc_u32 s63, s61, 0
	s_nop 0
	v_addc_co_u32_e32 v75, vcc, 0, v71, vcc
	v_lshl_add_u64 v[86:87], s[62:63], 0, v[114:115]
	v_add_co_u32_e32 v78, vcc, s81, v86
	s_and_b32 s49, s95, 1
	s_add_i32 s89, s1, 0xf0
	v_addc_co_u32_e32 v79, vcc, 0, v87, vcc
	s_cmp_eq_u32 s49, 0
	v_add_co_u32_e32 v82, vcc, s72, v86
	s_cselect_b64 s[76:77], -1, 0
	s_nop 0
	v_addc_co_u32_e32 v83, vcc, 0, v87, vcc
	s_and_b64 s[62:63], s[76:77], exec
	global_load_dwordx4 v[94:97], v[70:71], off
	global_load_dwordx4 v[98:101], v[70:71], off offset:1024
	s_nop 0
	global_load_dwordx4 v[70:73], v[74:75], off
	global_load_dwordx4 v[90:93], v[74:75], off offset:1024
	s_cselect_b32 s61, 0xf0, s89
	global_load_dwordx4 v[74:77], v[86:87], off
	v_add_co_u32_e32 v86, vcc, s73, v86
	v_and_b32_e32 v137, 63, v154
	v_lshl_add_u32 v137, v137, 2, s61
	s_nop 0
	v_addc_co_u32_e32 v87, vcc, 0, v87, vcc
	global_load_dwordx4 v[78:81], v[78:79], off
	s_nop 0
	global_load_dwordx4 v[82:85], v[82:83], off
	s_nop 0
	global_load_dwordx4 v[86:89], v[86:87], off
	ds_read2st64_b32 v[108:109], v137 offset1:1
	ds_read2st64_b32 v[142:143], v137 offset0:2 offset1:3
	s_waitcnt lgkmcnt(1)
	v_mfma_f32_16x16x4_f32 v[138:141], v108, v102, 0
	ds_read2st64_b32 v[146:147], v137 offset0:8 offset1:9
	v_mfma_f32_16x16x4_f32 v[138:141], v109, v103, v[138:141]
	s_waitcnt lgkmcnt(1)
	v_mfma_f32_16x16x4_f32 v[138:141], v142, v104, v[138:141]
	v_mfma_f32_16x16x4_f32 v[138:141], v143, v105, v[138:141]
	ds_read2st64_b32 v[142:143], v137 offset0:4 offset1:5
	s_nop 8
	v_add_f32_e32 v108, v106, v138
	v_min_f32_e32 v107, 0, v108
	v_mul_f32_e64 v108, |v108|, s66
	v_exp_f32_e32 v108, v108
	v_add_f32_e32 v109, v106, v139
	v_add_f32_e32 v135, v106, v140
	v_add_f32_e32 v138, v106, v141
	v_add_f32_e32 v108, 1.0, v108
	v_log_f32_e32 v108, v108
	s_nop 0
	v_fmac_f32_e32 v107, 0xbf317218, v108
	v_min_f32_e32 v108, 0, v109
	v_mul_f32_e64 v109, |v109|, s66
	v_exp_f32_e32 v109, v109
	v_fma_f32 v107, v107, s67, 0
	v_add_f32_e32 v109, 1.0, v109
	v_log_f32_e32 v109, v109
	s_nop 0
	v_fmac_f32_e32 v108, 0xbf317218, v109
	v_min_f32_e32 v109, 0, v135
	v_mul_f32_e64 v135, |v135|, s66
	v_exp_f32_e32 v135, v135
	v_fmamk_f32 v108, v108, 0x3d800000, v107
	v_add_f32_e32 v135, 1.0, v135
	v_log_f32_e32 v135, v135
	s_nop 0
	v_fmac_f32_e32 v109, 0xbf317218, v135
	v_min_f32_e32 v135, 0, v138
	v_mul_f32_e64 v138, |v138|, s66
	v_exp_f32_e32 v138, v138
	v_fmamk_f32 v109, v109, 0x3d800000, v108
	v_add_f32_e32 v138, 1.0, v138
	v_log_f32_e32 v138, v138
	s_nop 0
	v_fmac_f32_e32 v135, 0xbf317218, v138
	s_waitcnt lgkmcnt(0)
	v_mfma_f32_16x16x4_f32 v[138:141], v142, v102, 0
	v_fmamk_f32 v135, v135, 0x3d800000, v109
	v_mfma_f32_16x16x4_f32 v[138:141], v143, v103, v[138:141]
	ds_read2st64_b32 v[142:143], v137 offset0:6 offset1:7
	s_waitcnt lgkmcnt(0)
	v_mfma_f32_16x16x4_f32 v[138:141], v142, v104, v[138:141]
	v_mfma_f32_16x16x4_f32 v[138:141], v143, v105, v[138:141]
	s_nop 9
	v_add_f32_e32 v142, v106, v138
	v_min_f32_e32 v138, 0, v142
	v_mul_f32_e64 v142, |v142|, s66
	v_exp_f32_e32 v142, v142
	s_nop 0
	v_add_f32_e32 v142, 1.0, v142
	v_log_f32_e32 v142, v142
	s_nop 0
	v_fmac_f32_e32 v138, 0xbf317218, v142
	v_add_f32_e32 v142, v106, v139
	v_min_f32_e32 v139, 0, v142
	v_mul_f32_e64 v142, |v142|, s66
	v_exp_f32_e32 v142, v142
	s_nop 0
	v_add_f32_e32 v142, 1.0, v142
	v_log_f32_e32 v142, v142
	s_nop 0
	v_fmac_f32_e32 v139, 0xbf317218, v142
	v_add_f32_e32 v142, v106, v140
	v_min_f32_e32 v140, 0, v142
	v_mul_f32_e64 v142, |v142|, s66
	v_exp_f32_e32 v142, v142
	s_nop 0
	v_add_f32_e32 v142, 1.0, v142
	v_log_f32_e32 v142, v142
	s_nop 0
	v_fmac_f32_e32 v140, 0xbf317218, v142
	v_add_f32_e32 v142, v106, v141
	v_min_f32_e32 v141, 0, v142
	v_mul_f32_e64 v142, |v142|, s66
	v_exp_f32_e32 v142, v142
	s_nop 0
	v_add_f32_e32 v142, 1.0, v142
	v_log_f32_e32 v142, v142
	s_nop 0
	v_fmac_f32_e32 v141, 0xbf317218, v142
	v_mfma_f32_16x16x4_f32 v[142:145], v146, v102, 0
	v_mfma_f32_16x16x4_f32 v[142:145], v147, v103, v[142:145]
	ds_read2st64_b32 v[146:147], v137 offset0:10 offset1:11
	s_waitcnt lgkmcnt(0)
	v_mfma_f32_16x16x4_f32 v[142:145], v146, v104, v[142:145]
	v_mfma_f32_16x16x4_f32 v[142:145], v147, v105, v[142:145]
	ds_read2st64_b32 v[146:147], v137 offset0:12 offset1:13
	s_nop 8
	v_add_f32_e32 v142, v106, v142
	v_min_f32_e32 v148, 0, v142
	v_mul_f32_e64 v142, |v142|, s66
	v_exp_f32_e32 v142, v142
	s_nop 0
	v_add_f32_e32 v142, 1.0, v142
	v_log_f32_e32 v142, v142
	s_nop 0
	v_fmac_f32_e32 v148, 0xbf317218, v142
	v_add_f32_e32 v142, v106, v143
	v_min_f32_e32 v149, 0, v142
	v_mul_f32_e64 v142, |v142|, s66
	v_exp_f32_e32 v142, v142
	s_nop 0
	v_add_f32_e32 v142, 1.0, v142
	v_log_f32_e32 v142, v142
	s_nop 0
	v_fmac_f32_e32 v149, 0xbf317218, v142
	v_add_f32_e32 v142, v106, v144
	v_min_f32_e32 v150, 0, v142
	v_mul_f32_e64 v142, |v142|, s66
	v_exp_f32_e32 v142, v142
	s_nop 0
	v_add_f32_e32 v142, 1.0, v142
	v_log_f32_e32 v142, v142
	s_nop 0
	v_fmac_f32_e32 v150, 0xbf317218, v142
	v_add_f32_e32 v142, v106, v145
	v_min_f32_e32 v151, 0, v142
	v_mul_f32_e64 v142, |v142|, s66
	v_exp_f32_e32 v142, v142
	s_nop 0
	v_add_f32_e32 v142, 1.0, v142
	v_log_f32_e32 v142, v142
	s_nop 0
	v_fmac_f32_e32 v151, 0xbf317218, v142
	s_waitcnt lgkmcnt(0)
	v_mfma_f32_16x16x4_f32 v[142:145], v146, v102, 0
	v_mfma_f32_16x16x4_f32 v[142:145], v147, v103, v[142:145]
	ds_read2st64_b32 v[146:147], v137 offset0:14 offset1:15
	s_waitcnt lgkmcnt(0)
	v_mfma_f32_16x16x4_f32 v[142:145], v146, v104, v[142:145]
	v_mfma_f32_16x16x4_f32 v[142:145], v147, v105, v[142:145]
	s_nop 9
	v_add_f32_e32 v137, v106, v142
	v_min_f32_e32 v142, 0, v137
	v_mul_f32_e64 v137, |v137|, s66
	v_exp_f32_e32 v137, v137
	s_nop 0
	v_add_f32_e32 v137, 1.0, v137
	v_log_f32_e32 v137, v137
	s_nop 0
	v_fmac_f32_e32 v142, 0xbf317218, v137
	v_add_f32_e32 v137, v106, v143
	v_min_f32_e32 v143, 0, v137
	v_mul_f32_e64 v137, |v137|, s66
	v_exp_f32_e32 v137, v137
	s_nop 0
	v_add_f32_e32 v137, 1.0, v137
	v_log_f32_e32 v137, v137
	s_nop 0
	v_fmac_f32_e32 v143, 0xbf317218, v137
	v_add_f32_e32 v137, v106, v144
	v_min_f32_e32 v144, 0, v137
	v_mul_f32_e64 v137, |v137|, s66
	v_exp_f32_e32 v137, v137
	s_nop 0
	v_add_f32_e32 v137, 1.0, v137
	v_log_f32_e32 v137, v137
	s_nop 0
	v_fmac_f32_e32 v144, 0xbf317218, v137
	v_add_f32_e32 v137, v106, v145
	v_min_f32_e32 v145, 0, v137
	v_mul_f32_e64 v137, |v137|, s66
	v_exp_f32_e32 v137, v137
	s_nop 0
	v_add_f32_e32 v137, 1.0, v137
	v_log_f32_e32 v137, v137
	s_nop 0
	v_fmac_f32_e32 v145, 0xbf317218, v137
	v_fmamk_f32 v137, v138, 0x3d800000, v135
	v_fmamk_f32 v138, v139, 0x3d800000, v137
	v_fmamk_f32 v139, v140, 0x3d800000, v138
	v_fmamk_f32 v140, v141, 0x3d800000, v139
	v_fmamk_f32 v141, v148, 0x3d800000, v140
	v_fmamk_f32 v146, v149, 0x3d800000, v141
	v_fmamk_f32 v147, v150, 0x3d800000, v146
	v_fmamk_f32 v148, v151, 0x3d800000, v147
	v_fmamk_f32 v142, v142, 0x3d800000, v148
	v_fmamk_f32 v143, v143, 0x3d800000, v142
	v_fmamk_f32 v144, v144, 0x3d800000, v143
	v_fmamk_f32 v145, v145, 0x3d800000, v144
	ds_bpermute_b32 v149, v190, v145
	ds_bpermute_b32 v150, v191, v145
	ds_bpermute_b32 v151, v192, v145
	s_waitcnt lgkmcnt(2)
	v_cndmask_b32_e64 v149, v149, 0, s[4:5]
	s_waitcnt lgkmcnt(1)
	v_cndmask_b32_e64 v150, 0, v150, s[6:7]
	v_add_f32_e32 v149, v149, v150
	s_waitcnt lgkmcnt(0)
	v_cndmask_b32_e64 v150, 0, v151, s[8:9]
	v_add_f32_e32 v149, v149, v150
	v_add_f32_e32 v107, v107, v149
	v_add_f32_e32 v108, v108, v149
	ds_write2st64_b32 v204, v107, v108 offset0:24 offset1:26
	v_add_f32_e32 v107, v109, v149
	v_add_f32_e32 v108, v135, v149
	ds_write2st64_b32 v204, v107, v108 offset0:28 offset1:30
	v_add_f32_e32 v107, v137, v149
	v_add_f32_e32 v108, v138, v149
	ds_write2st64_b32 v204, v107, v108 offset0:32 offset1:34
	v_add_f32_e32 v107, v139, v149
	v_add_f32_e32 v108, v140, v149
	ds_write2st64_b32 v204, v107, v108 offset0:36 offset1:38
	v_add_f32_e32 v107, v141, v149
	v_add_f32_e32 v108, v146, v149
	ds_write2st64_b32 v204, v107, v108 offset0:40 offset1:42
	v_add_f32_e32 v107, v149, v147
	v_add_f32_e32 v108, v149, v148
	ds_write2st64_b32 v204, v107, v108 offset0:44 offset1:46
	v_add_f32_e32 v107, v149, v142
	v_add_f32_e32 v108, v149, v143
	ds_write2st64_b32 v204, v107, v108 offset0:48 offset1:50
	v_add_f32_e32 v107, v149, v144
	v_add_f32_e32 v108, v149, v145
	ds_write2st64_b32 v204, v107, v108 offset0:52 offset1:54
	s_waitcnt lgkmcnt(0)
	s_barrier
	s_and_saveexec_b64 s[62:63], s[10:11]
	s_cbranch_execz .LBB0_2269
	ds_read_b32 v107, v181 offset:38400
	v_lshl_add_u32 v108, s49, 9, v181
	s_waitcnt lgkmcnt(0)
	ds_write_b32 v108, v107 offset:4096
.LBB0_2269:
	s_or_b64 exec, exec, s[62:63]
	s_cmp_gt_u32 s95, 6
	s_cbranch_scc1 .LBB0_2266
	s_and_saveexec_b64 s[62:63], s[2:3]
	s_and_b64 s[70:71], s[76:77], exec
	s_cselect_b32 s61, s89, 0xf0
	v_add_u32_e32 v107, s61, v250
	ds_write2_b32 v107, v2, v3 offset1:16
	ds_write2_b32 v107, v4, v5 offset0:32 offset1:48
	s_or_b64 exec, exec, s[62:63]
	s_cmp_eq_u32 s74, 0x240000
	s_cbranch_scc1 .LBB0_2266
	s_ashr_i32 s61, s60, 31
	s_lshl_b64 s[62:63], s[60:61], 7
	s_add_u32 s70, s84, s62
	s_addc_u32 s71, s85, s63
	s_and_saveexec_b64 s[62:63], s[2:3]
	s_cbranch_execz .LBB0_2265
	v_lshl_add_u64 v[2:3], s[70:71], 0, v[110:111]
	global_load_dwordx4 v[2:5], v[2:3], off
	s_branch .LBB0_2265

.LBB0_2277:
	s_or_b64 exec, exec, s[60:61]
	s_and_saveexec_b64 s[58:59], s[2:3]
	s_cbranch_execz .LBB0_2279
	s_waitcnt vmcnt(0)
	v_add_u32_e32 v251, 0xf0, v250
	ds_write2_b32 v251, v2, v3 offset1:16
	ds_write2_b32 v251, v4, v5 offset0:32 offset1:48

.LBB0_2283:
	s_add_u32 s60, s70, s58
	s_addc_u32 s61, s71, s59
	s_add_u32 s49, s64, s58
	s_addc_u32 s69, s65, s59
	s_add_u32 s53, s49, s0
	v_lshl_add_u64 v[70:71], s[60:61], 0, v[112:113]
	s_addc_u32 s61, s69, 0
	s_add_u32 s60, s53, 0xafc0800
	v_add_co_u32_e32 v74, vcc, s72, v70
	s_addc_u32 s61, s61, 0
	s_nop 0
	v_addc_co_u32_e32 v75, vcc, 0, v71, vcc
	v_lshl_add_u64 v[86:87], s[60:61], 0, v[114:115]
	v_add_co_u32_e32 v78, vcc, s81, v86
	s_and_b32 s68, s74, 1
	s_nop 0
	v_addc_co_u32_e32 v79, vcc, 0, v87, vcc
	s_cmp_eq_u32 s68, 0
	v_add_co_u32_e32 v82, vcc, s72, v86
	s_cselect_b64 s[60:61], -1, 0
	s_nop 0
	v_addc_co_u32_e32 v83, vcc, 0, v87, vcc
	s_and_b64 s[62:63], s[60:61], exec
	global_load_dwordx4 v[94:97], v[70:71], off
	global_load_dwordx4 v[98:101], v[70:71], off offset:1024
	s_nop 0
	global_load_dwordx4 v[70:73], v[74:75], off
	global_load_dwordx4 v[90:93], v[74:75], off offset:1024
	s_cselect_b32 s53, 0xf0, s89
	global_load_dwordx4 v[74:77], v[86:87], off
	v_add_co_u32_e32 v86, vcc, s73, v86
	v_and_b32_e32 v105, 63, v154
	v_lshl_add_u32 v105, v105, 2, s53
	s_nop 0
	v_addc_co_u32_e32 v87, vcc, 0, v87, vcc
	global_load_dwordx4 v[78:81], v[78:79], off
	s_nop 0
	global_load_dwordx4 v[82:85], v[82:83], off
	s_nop 0
	global_load_dwordx4 v[86:89], v[86:87], off
	ds_read2st64_b32 v[102:103], v105 offset1:1
	ds_read2st64_b32 v[140:141], v105 offset0:2 offset1:3
	s_waitcnt vmcnt(12) lgkmcnt(1)
	v_mfma_f32_16x16x4_f32 v[106:109], v102, v223, 0
	ds_read2st64_b32 v[144:145], v105 offset0:8 offset1:9
	s_waitcnt vmcnt(11)
	v_mfma_f32_16x16x4_f32 v[106:109], v103, v224, v[106:109]
	s_waitcnt vmcnt(10) lgkmcnt(1)
	v_mfma_f32_16x16x4_f32 v[106:109], v140, v225, v[106:109]
	s_waitcnt vmcnt(9)
	v_mfma_f32_16x16x4_f32 v[106:109], v141, v226, v[106:109]
	ds_read2st64_b32 v[140:141], v105 offset0:4 offset1:5
	s_waitcnt vmcnt(8)
	s_nop 7
	v_add_f32_e32 v102, v227, v106
	v_min_f32_e32 v0, 0, v102
	v_mul_f32_e64 v102, |v102|, s66
	v_exp_f32_e32 v102, v102
	v_add_f32_e32 v103, v227, v107
	v_add_f32_e32 v104, v227, v108
	v_add_f32_e32 v106, v227, v109
	v_add_f32_e32 v102, 1.0, v102
	v_log_f32_e32 v102, v102
	s_nop 0
	v_fmac_f32_e32 v0, 0xbf317218, v102
	v_min_f32_e32 v102, 0, v103
	v_mul_f32_e64 v103, |v103|, s66
	v_exp_f32_e32 v103, v103
	s_nop 0
	v_add_f32_e32 v103, 1.0, v103
	v_log_f32_e32 v103, v103
	s_nop 0
	v_fmac_f32_e32 v102, 0xbf317218, v103
	v_min_f32_e32 v103, 0, v104
	v_mul_f32_e64 v104, |v104|, s66
	v_exp_f32_e32 v104, v104
	s_nop 0
	v_add_f32_e32 v104, 1.0, v104
	v_log_f32_e32 v104, v104
	s_nop 0
	v_fmac_f32_e32 v103, 0xbf317218, v104
	v_min_f32_e32 v104, 0, v106
	v_mul_f32_e64 v106, |v106|, s66
	v_exp_f32_e32 v106, v106
	s_nop 0
	v_add_f32_e32 v106, 1.0, v106
	v_log_f32_e32 v106, v106
	s_nop 0
	v_fmac_f32_e32 v104, 0xbf317218, v106
	s_waitcnt lgkmcnt(0)
	v_mfma_f32_16x16x4_f32 v[106:109], v140, v223, 0
	v_mfma_f32_16x16x4_f32 v[106:109], v141, v224, v[106:109]
	ds_read2st64_b32 v[140:141], v105 offset0:6 offset1:7
	s_waitcnt lgkmcnt(0)
	v_mfma_f32_16x16x4_f32 v[106:109], v140, v225, v[106:109]
	v_mfma_f32_16x16x4_f32 v[106:109], v141, v226, v[106:109]
	v_mfma_f32_16x16x4_f32 v[140:143], v144, v223, 0
	s_nop 8
	v_add_f32_e32 v135, v227, v106
	v_min_f32_e32 v106, 0, v135
	v_mul_f32_e64 v135, |v135|, s66
	v_exp_f32_e32 v135, v135
	s_nop 0
	v_add_f32_e32 v135, 1.0, v135
	v_log_f32_e32 v135, v135
	v_mfma_f32_16x16x4_f32 v[140:143], v145, v224, v[140:143]
	ds_read2st64_b32 v[144:145], v105 offset0:10 offset1:11
	v_fmac_f32_e32 v106, 0xbf317218, v135
	v_add_f32_e32 v135, v227, v107
	v_min_f32_e32 v107, 0, v135
	v_mul_f32_e64 v135, |v135|, s66
	v_exp_f32_e32 v135, v135
	s_waitcnt lgkmcnt(0)
	v_mfma_f32_16x16x4_f32 v[140:143], v144, v225, v[140:143]
	v_add_f32_e32 v135, 1.0, v135
	v_log_f32_e32 v135, v135
	s_nop 0
	v_fmac_f32_e32 v107, 0xbf317218, v135
	v_add_f32_e32 v135, v227, v108
	v_min_f32_e32 v108, 0, v135
	v_mul_f32_e64 v135, |v135|, s66
	v_exp_f32_e32 v135, v135
	v_mfma_f32_16x16x4_f32 v[140:143], v145, v226, v[140:143]
	ds_read2st64_b32 v[144:145], v105 offset0:12 offset1:13
	v_add_f32_e32 v135, 1.0, v135
	v_log_f32_e32 v135, v135
	s_nop 0
	v_fmac_f32_e32 v108, 0xbf317218, v135
	v_add_f32_e32 v135, v227, v109
	v_min_f32_e32 v109, 0, v135
	v_mul_f32_e64 v135, |v135|, s66
	v_exp_f32_e32 v135, v135
	s_nop 0
	v_add_f32_e32 v135, 1.0, v135
	v_log_f32_e32 v135, v135
	s_nop 0
	v_fmac_f32_e32 v109, 0xbf317218, v135
	v_add_f32_e32 v135, v227, v140
	v_min_f32_e32 v137, 0, v135
	v_mul_f32_e64 v135, |v135|, s66
	v_exp_f32_e32 v135, v135
	s_nop 0
	v_add_f32_e32 v135, 1.0, v135
	v_log_f32_e32 v135, v135
	s_nop 0
	v_fmac_f32_e32 v137, 0xbf317218, v135
	v_add_f32_e32 v135, v227, v141
	v_min_f32_e32 v146, 0, v135
	v_mul_f32_e64 v135, |v135|, s66
	v_exp_f32_e32 v135, v135
	s_nop 0
	v_add_f32_e32 v135, 1.0, v135
	v_log_f32_e32 v135, v135
	s_nop 0
	v_fmac_f32_e32 v146, 0xbf317218, v135
	v_add_f32_e32 v135, v227, v142
	v_min_f32_e32 v147, 0, v135
	v_mul_f32_e64 v135, |v135|, s66
	v_exp_f32_e32 v135, v135
	s_nop 0
	v_add_f32_e32 v135, 1.0, v135
	v_log_f32_e32 v135, v135
	s_nop 0
	v_fmac_f32_e32 v147, 0xbf317218, v135
	v_add_f32_e32 v135, v227, v143
	s_waitcnt lgkmcnt(0)
	v_mfma_f32_16x16x4_f32 v[140:143], v144, v223, 0
	v_min_f32_e32 v148, 0, v135
	v_mul_f32_e64 v135, |v135|, s66
	v_exp_f32_e32 v135, v135
	s_nop 0
	v_add_f32_e32 v135, 1.0, v135
	v_mfma_f32_16x16x4_f32 v[140:143], v145, v224, v[140:143]
	ds_read2st64_b32 v[144:145], v105 offset0:14 offset1:15
	v_log_f32_e32 v135, v135
	s_nop 0
	v_fmac_f32_e32 v148, 0xbf317218, v135
	s_waitcnt lgkmcnt(0)
	v_mfma_f32_16x16x4_f32 v[140:143], v144, v225, v[140:143]
	v_mfma_f32_16x16x4_f32 v[140:143], v145, v226, v[140:143]
	s_nop 9
	v_add_f32_e32 v105, v227, v140
	v_min_f32_e32 v135, 0, v105
	v_mul_f32_e64 v105, |v105|, s66
	v_exp_f32_e32 v105, v105
	s_nop 0
	v_add_f32_e32 v105, 1.0, v105
	v_log_f32_e32 v105, v105
	s_nop 0
	v_fmac_f32_e32 v135, 0xbf317218, v105
	v_add_f32_e32 v105, v227, v141
	v_min_f32_e32 v140, 0, v105
	v_mul_f32_e64 v105, |v105|, s66
	v_exp_f32_e32 v105, v105
	s_nop 0
	v_add_f32_e32 v105, 1.0, v105
	v_log_f32_e32 v105, v105
	s_nop 0
	v_fmac_f32_e32 v140, 0xbf317218, v105
	v_add_f32_e32 v105, v227, v142
	v_min_f32_e32 v141, 0, v105
	v_mul_f32_e64 v105, |v105|, s66
	v_exp_f32_e32 v105, v105
	s_nop 0
	v_add_f32_e32 v105, 1.0, v105
	v_log_f32_e32 v105, v105
	s_nop 0
	v_fmac_f32_e32 v141, 0xbf317218, v105
	v_add_f32_e32 v105, v227, v143
	v_min_f32_e32 v142, 0, v105
	v_mul_f32_e64 v105, |v105|, s66
	v_exp_f32_e32 v105, v105
	s_nop 0
	v_add_f32_e32 v105, 1.0, v105
	v_log_f32_e32 v105, v105
	s_nop 0
	v_fmac_f32_e32 v142, 0xbf317218, v105
	v_fma_f32 v105, v142, s67, 0
	v_fmamk_f32 v141, v141, 0x3d800000, v105
	v_fmamk_f32 v140, v140, 0x3d800000, v141
	v_fmamk_f32 v135, v135, 0x3d800000, v140
	v_fmamk_f32 v142, v148, 0x3d800000, v135
	v_fmamk_f32 v143, v147, 0x3d800000, v142
	v_fmamk_f32 v144, v146, 0x3d800000, v143
	v_fmamk_f32 v137, v137, 0x3d800000, v144
	v_fmamk_f32 v109, v109, 0x3d800000, v137
	v_fmamk_f32 v108, v108, 0x3d800000, v109
	v_fmamk_f32 v107, v107, 0x3d800000, v108
	v_fmamk_f32 v106, v106, 0x3d800000, v107
	v_fmamk_f32 v104, v104, 0x3d800000, v106
	v_fmamk_f32 v103, v103, 0x3d800000, v104
	v_fmamk_f32 v102, v102, 0x3d800000, v103
	v_fmamk_f32 v0, v0, 0x3d800000, v102
	ds_bpermute_b32 v146, v192, v0
	ds_bpermute_b32 v147, v193, v0
	ds_bpermute_b32 v145, v191, v0
	s_waitcnt lgkmcnt(2)
	v_cndmask_b32_e64 v146, 0, v146, s[28:29]
	s_waitcnt lgkmcnt(1)
	v_cndmask_b32_e64 v147, v147, 0, s[8:9]
	v_add_f32_e32 v146, v146, v147
	s_waitcnt lgkmcnt(0)
	v_cndmask_b32_e64 v145, 0, v145, s[4:5]
	v_add_f32_e32 v145, v145, v146
	v_add_f32_e32 v0, v145, v0
	v_add_f32_e32 v102, v145, v102
	ds_write2st64_b32 v204, v0, v102 offset0:24 offset1:26
	v_add_f32_e32 v0, v145, v103
	v_add_f32_e32 v102, v145, v104
	ds_write2st64_b32 v204, v0, v102 offset0:28 offset1:30
	v_add_f32_e32 v0, v145, v106
	v_add_f32_e32 v102, v145, v107
	ds_write2st64_b32 v204, v0, v102 offset0:32 offset1:34
	v_add_f32_e32 v0, v145, v108
	v_add_f32_e32 v102, v145, v109
	ds_write2st64_b32 v204, v0, v102 offset0:36 offset1:38
	v_add_f32_e32 v0, v145, v137
	v_add_f32_e32 v102, v145, v144
	ds_write2st64_b32 v204, v0, v102 offset0:40 offset1:42
	v_add_f32_e32 v0, v145, v143
	v_add_f32_e32 v102, v145, v142
	ds_write2st64_b32 v204, v0, v102 offset0:44 offset1:46
	v_add_f32_e32 v0, v145, v135
	v_add_f32_e32 v102, v145, v140
	ds_write2st64_b32 v204, v0, v102 offset0:48 offset1:50
	v_add_f32_e32 v0, v145, v141
	v_add_f32_e32 v102, v145, v105
	ds_write2st64_b32 v204, v0, v102 offset0:52 offset1:54
	s_waitcnt lgkmcnt(0)
	s_barrier
	s_and_saveexec_b64 s[62:63], s[10:11]
	s_cbranch_execz .LBB0_2285
	ds_read_b32 v0, v181 offset:6144
	v_lshl_add_u32 v102, s68, 9, v181
	s_waitcnt lgkmcnt(0)
	ds_write_b32 v102, v0 offset:4096
.LBB0_2285:
	s_or_b64 exec, exec, s[62:63]
	s_cmp_gt_u32 s74, 6
	s_cbranch_scc1 .LBB0_2292
	s_and_saveexec_b64 s[62:63], s[2:3]
	s_and_b64 s[60:61], s[60:61], exec
	s_cselect_b32 s53, s89, 0xf0
	v_add_u32_e32 v0, s53, v250
	ds_write2_b32 v0, v2, v3 offset1:16
	ds_write2_b32 v0, v4, v5 offset0:32 offset1:48
	s_or_b64 exec, exec, s[62:63]
	s_cmp_eq_u32 s58, 0xffdc0000
	s_cbranch_scc1 .LBB0_2292
	s_ashr_i32 s53, s52, 31
	s_lshl_b64 s[60:61], s[52:53], 7
	s_add_u32 s53, s79, s60
	s_addc_u32 s60, s78, s61
	s_add_u32 s62, s53, 0x2100040
	s_addc_u32 s63, s60, 0
	s_and_saveexec_b64 s[60:61], s[2:3]
	s_cbranch_execz .LBB0_2291
	v_lshl_add_u64 v[2:3], s[62:63], 0, v[110:111]
	global_load_dwordx4 v[2:5], v[2:3], off
